# GEMM1 main loop rewritten with LDS-DMA staging + scan S-update LDS reads hoisted
# speedup vs baseline: 1.0114x; 1.0114x over previous
.LBB0_330:
	s_andn2_saveexec_b64 s[0:1], s[0:1]
	s_or_b64 exec, exec, s[0:1]
	v_cvt_pk_bf16_f32 v90, v90, v91
	v_cvt_pk_bf16_f32 v91, v92, v93
	v_add_u32_e32 v92, v210, v154
	v_add_u32_e32 v94, v202, v200
	ds_write_b64 v92, v[90:91] offset:40960
	s_waitcnt lgkmcnt(0)
	s_barrier
	ds_read_b128 v[102:105], v94 offset:24576
	v_add_u32_e32 v95, v202, v201
	ds_read_b128 v[90:93], v95 offset:24576
	ds_read_b128 v[98:101], v94 offset:26624
	ds_read_b128 v[94:97], v95 offset:26624
	ds_read_b128 v[210:213], v209 offset:40960
	ds_read_b128 v[218:221], v209 offset:43008
	ds_read_b128 v[242:245], v2 offset:40960
	s_waitcnt lgkmcnt(2)
	v_mfma_f32_16x16x32_bf16 v[214:217], v[102:105], v[210:213], 0
	ds_read_b128 v[226:229], v209 offset:45056
	ds_read_b128 v[234:237], v209 offset:47104
	v_ashrrev_i32_e32 v135, 31, v134
	v_mfma_f32_16x16x32_bf16 v[210:213], v[98:101], v[210:213], 0
	s_mov_b64 s[0:1], -1
	s_and_b64 vcc, exec, s[4:5]
	s_waitcnt lgkmcnt(2)
	v_mfma_f32_16x16x32_bf16 v[214:217], v[90:93], v[242:245], v[214:217]
	v_mfma_f32_16x16x32_bf16 v[210:213], v[94:97], v[242:245], v[210:213]
	ds_read_b128 v[242:245], v2 offset:43008
	v_mfma_f32_16x16x32_bf16 v[222:225], v[102:105], v[218:221], 0
	v_mfma_f32_16x16x32_bf16 v[218:221], v[98:101], v[218:221], 0
	s_waitcnt lgkmcnt(0)
	v_mfma_f32_16x16x32_bf16 v[222:225], v[90:93], v[242:245], v[222:225]
	v_mfma_f32_16x16x32_bf16 v[218:221], v[94:97], v[242:245], v[218:221]
	ds_read_b128 v[242:245], v2 offset:45056
	v_mfma_f32_16x16x32_bf16 v[230:233], v[102:105], v[226:229], 0
	v_mfma_f32_16x16x32_bf16 v[226:229], v[98:101], v[226:229], 0
	s_waitcnt lgkmcnt(0)
	v_mfma_f32_16x16x32_bf16 v[230:233], v[90:93], v[242:245], v[230:233]
	v_mfma_f32_16x16x32_bf16 v[226:229], v[94:97], v[242:245], v[226:229]
	ds_read_b128 v[242:245], v2 offset:47104
	v_mfma_f32_16x16x32_bf16 v[238:241], v[102:105], v[234:237], 0
	v_mfma_f32_16x16x32_bf16 v[234:237], v[98:101], v[234:237], 0
	s_waitcnt lgkmcnt(0)
	v_mfma_f32_16x16x32_bf16 v[238:241], v[90:93], v[242:245], v[238:241]
	v_mfma_f32_16x16x32_bf16 v[234:237], v[94:97], v[242:245], v[234:237]
	ds_read_b128 v[242:245], v206 offset:49152
	ds_read_b128 v[246:249], v206 offset:51200
	ds_read_b128 v[250:253], v209
	s_waitcnt lgkmcnt(0)
	v_mfma_f32_16x16x32_bf16 v[214:217], v[242:245], v[250:253], v[214:217]
	v_mfma_f32_16x16x32_bf16 v[210:213], v[246:249], v[250:253], v[210:213]
	ds_read_b128 v[250:253], v209 offset:2048
	s_waitcnt lgkmcnt(0)
	v_mfma_f32_16x16x32_bf16 v[222:225], v[242:245], v[250:253], v[222:225]
	v_mfma_f32_16x16x32_bf16 v[218:221], v[246:249], v[250:253], v[218:221]
	ds_read_b128 v[250:253], v209 offset:4096
	s_waitcnt lgkmcnt(0)
	v_mfma_f32_16x16x32_bf16 v[230:233], v[242:245], v[250:253], v[230:233]
	v_mfma_f32_16x16x32_bf16 v[226:229], v[246:249], v[250:253], v[226:229]
	ds_read_b128 v[250:253], v209 offset:6144
	s_waitcnt lgkmcnt(0)
	v_mfma_f32_16x16x32_bf16 v[238:241], v[242:245], v[250:253], v[238:241]
	v_mfma_f32_16x16x32_bf16 v[234:237], v[246:249], v[250:253], v[234:237]
	ds_read_b128 v[242:245], v207 offset:49152
	ds_read_b128 v[246:249], v207 offset:51200
	ds_read_b128 v[250:253], v2
	s_waitcnt lgkmcnt(0)
	v_mfma_f32_16x16x32_bf16 v[214:217], v[242:245], v[250:253], v[214:217]
	v_mfma_f32_16x16x32_bf16 v[210:213], v[246:249], v[250:253], v[210:213]
	ds_read_b128 v[250:253], v2 offset:2048
	s_nop 5
	v_cvt_pk_bf16_f32 v214, v214, v215
	v_cvt_pk_bf16_f32 v215, v216, v217
	s_waitcnt lgkmcnt(0)
	v_mfma_f32_16x16x32_bf16 v[222:225], v[242:245], v[250:253], v[222:225]
	v_cvt_pk_bf16_f32 v210, v210, v211
	v_mfma_f32_16x16x32_bf16 v[218:221], v[246:249], v[250:253], v[218:221]
	ds_read_b128 v[250:253], v2 offset:4096
	v_cvt_pk_bf16_f32 v211, v212, v213
	s_waitcnt lgkmcnt(0)
	v_mfma_f32_16x16x32_bf16 v[230:233], v[242:245], v[250:253], v[230:233]
	v_mfma_f32_16x16x32_bf16 v[226:229], v[246:249], v[250:253], v[226:229]
	ds_read_b128 v[250:253], v2 offset:6144
	s_waitcnt lgkmcnt(0)
	v_mfma_f32_16x16x32_bf16 v[238:241], v[242:245], v[250:253], v[238:241]
	v_subrev_u32_e32 v242, 48, v134
	v_ashrrev_i32_e32 v243, 31, v242
	v_lshlrev_b64 v[216:217], 11, v[242:243]
	v_lshl_add_u64 v[216:217], v[132:133], 0, v[216:217]
	global_store_dwordx2 v[216:217], v[214:215], off
	v_cvt_pk_bf16_f32 v214, v222, v223
	v_subrev_u32_e32 v222, 32, v134
	v_mfma_f32_16x16x32_bf16 v[234:237], v[246:249], v[250:253], v[234:237]
	v_cvt_pk_bf16_f32 v215, v224, v225
	v_ashrrev_i32_e32 v223, 31, v222
	v_add_u32_e32 v224, -16, v134
	v_lshlrev_b64 v[222:223], 11, v[222:223]
	v_ashrrev_i32_e32 v225, 31, v224
	v_lshl_add_u64 v[222:223], v[132:133], 0, v[222:223]
	v_lshlrev_b64 v[224:225], 11, v[224:225]
	global_store_dwordx2 v[216:217], v[210:211], off offset:32
	v_cvt_pk_bf16_f32 v210, v218, v219
	v_cvt_pk_bf16_f32 v211, v220, v221
	global_store_dwordx2 v[222:223], v[214:215], off
	v_cvt_pk_bf16_f32 v214, v230, v231
	v_cvt_pk_bf16_f32 v215, v232, v233
	v_lshl_add_u64 v[224:225], v[132:133], 0, v[224:225]
	v_lshlrev_b64 v[230:231], 11, v[134:135]
	global_store_dwordx2 v[222:223], v[210:211], off offset:32
	v_cvt_pk_bf16_f32 v210, v226, v227
	v_cvt_pk_bf16_f32 v211, v228, v229
	global_store_dwordx2 v[224:225], v[214:215], off
	v_cvt_pk_bf16_f32 v214, v238, v239
	v_cvt_pk_bf16_f32 v215, v240, v241
	v_lshl_add_u64 v[230:231], v[132:133], 0, v[230:231]
	global_store_dwordx2 v[224:225], v[210:211], off offset:32
	v_cvt_pk_bf16_f32 v210, v234, v235
	v_cvt_pk_bf16_f32 v211, v236, v237
	global_store_dwordx2 v[230:231], v[214:215], off
	global_store_dwordx2 v[230:231], v[210:211], off offset:32
	ds_read_b128 v[218:221], v208
	ds_read_b128 v[222:225], v208 offset:64
	ds_read_b128 v[226:229], v208 offset:128
	ds_read_b128 v[230:233], v208 offset:192
	ds_read_b128 v[234:237], v209 offset:16384
	ds_read_b128 v[238:241], v209 offset:18432
	ds_read_b128 v[242:245], v209 offset:20480
	ds_read_b128 v[246:249], v209 offset:22528
	ds_read_b128 v[250:253], v2 offset:16384
	s_waitcnt lgkmcnt(8)
	v_pk_mul_f32 v[22:23], v[22:23], v[218:219]
	v_pk_mul_f32 v[24:25], v[24:25], v[220:221]
	v_pk_mul_f32 v[26:27], v[26:27], v[218:219]
	v_pk_mul_f32 v[28:29], v[28:29], v[220:221]
	s_waitcnt lgkmcnt(7)
	v_pk_mul_f32 v[30:31], v[30:31], v[222:223]
	v_pk_mul_f32 v[32:33], v[32:33], v[224:225]
	v_pk_mul_f32 v[34:35], v[34:35], v[222:223]
	v_pk_mul_f32 v[36:37], v[36:37], v[224:225]
	s_waitcnt lgkmcnt(6)
	v_pk_mul_f32 v[38:39], v[38:39], v[226:227]
	v_pk_mul_f32 v[40:41], v[40:41], v[228:229]
	v_pk_mul_f32 v[42:43], v[42:43], v[226:227]
	v_pk_mul_f32 v[44:45], v[44:45], v[228:229]
	s_waitcnt lgkmcnt(5)
	v_pk_mul_f32 v[46:47], v[46:47], v[230:231]
	v_pk_mul_f32 v[48:49], v[48:49], v[232:233]
	v_pk_mul_f32 v[50:51], v[50:51], v[230:231]
	v_pk_mul_f32 v[52:53], v[52:53], v[232:233]
	ds_read_b128 v[218:221], v2 offset:18432
	ds_read_b128 v[222:225], v2 offset:20480
	ds_read_b128 v[226:229], v2 offset:22528
	s_waitcnt lgkmcnt(7)
	v_mfma_f32_16x16x32_bf16 v[22:25], v[234:237], v[102:105], v[22:25]
	v_mfma_f32_16x16x32_bf16 v[26:29], v[234:237], v[98:101], v[26:29]
	s_waitcnt lgkmcnt(6)
	v_mfma_f32_16x16x32_bf16 v[30:33], v[238:241], v[102:105], v[30:33]
	v_mfma_f32_16x16x32_bf16 v[34:37], v[238:241], v[98:101], v[34:37]
	s_waitcnt lgkmcnt(5)
	v_mfma_f32_16x16x32_bf16 v[38:41], v[242:245], v[102:105], v[38:41]
	v_mfma_f32_16x16x32_bf16 v[42:45], v[242:245], v[98:101], v[42:45]
	s_waitcnt lgkmcnt(4)
	v_mfma_f32_16x16x32_bf16 v[46:49], v[246:249], v[102:105], v[46:49]
	v_mfma_f32_16x16x32_bf16 v[50:53], v[246:249], v[98:101], v[50:53]
	s_waitcnt lgkmcnt(3)
	v_mfma_f32_16x16x32_bf16 v[22:25], v[250:253], v[90:93], v[22:25]
	v_mfma_f32_16x16x32_bf16 v[26:29], v[250:253], v[94:97], v[26:29]
	s_waitcnt lgkmcnt(2)
	v_mfma_f32_16x16x32_bf16 v[30:33], v[218:221], v[90:93], v[30:33]
	v_mfma_f32_16x16x32_bf16 v[34:37], v[218:221], v[94:97], v[34:37]
	s_waitcnt lgkmcnt(1)
	v_mfma_f32_16x16x32_bf16 v[38:41], v[222:225], v[90:93], v[38:41]
	v_mfma_f32_16x16x32_bf16 v[42:45], v[222:225], v[94:97], v[42:45]
	s_waitcnt lgkmcnt(0)
	v_mfma_f32_16x16x32_bf16 v[46:49], v[226:229], v[90:93], v[46:49]
	v_mfma_f32_16x16x32_bf16 v[50:53], v[226:229], v[94:97], v[50:53]
	s_nop 1
	v_cvt_pk_bf16_f32 v90, v22, v23
	v_cvt_pk_bf16_f32 v91, v24, v25
	v_cvt_pk_bf16_f32 v92, v26, v27
	v_cvt_pk_bf16_f32 v93, v28, v29
	ds_write2st64_b64 v146, v[90:91], v[92:93] offset0:96 offset1:100
	v_cvt_pk_bf16_f32 v90, v30, v31
	v_cvt_pk_bf16_f32 v91, v32, v33
	v_cvt_pk_bf16_f32 v92, v34, v35
	v_cvt_pk_bf16_f32 v93, v36, v37
	ds_write2st64_b64 v149, v[90:91], v[92:93] offset0:96 offset1:100
	v_cvt_pk_bf16_f32 v90, v38, v39
	v_cvt_pk_bf16_f32 v91, v40, v41
	v_cvt_pk_bf16_f32 v92, v42, v43
	v_cvt_pk_bf16_f32 v93, v44, v45
	ds_write2st64_b64 v152, v[90:91], v[92:93] offset0:96 offset1:100
	v_cvt_pk_bf16_f32 v90, v46, v47
	v_cvt_pk_bf16_f32 v91, v48, v49
	v_cvt_pk_bf16_f32 v92, v50, v51
	v_cvt_pk_bf16_f32 v93, v52, v53
	ds_write2st64_b64 v155, v[90:91], v[92:93] offset0:96 offset1:100
	s_waitcnt lgkmcnt(0)
	s_barrier
	s_cbranch_vccnz .LBB0_332
	s_mov_b64 s[0:1], 0
	s_waitcnt vmcnt(16)
	ds_write_b128 v156, v[86:89]
	s_waitcnt vmcnt(15)
	ds_write_b128 v156, v[82:85] offset:8192
	s_waitcnt vmcnt(14)
	ds_write_b128 v156, v[78:81] offset:4096
	s_waitcnt vmcnt(13)
	ds_write_b128 v156, v[74:77] offset:12288

.LBB0_346:
	v_and_b32_e32 v76, 63, v0
	v_lshrrev_b32_e32 v77, 6, v0
	v_and_b32_e32 v93, 15, v0
	v_readfirstlane_b32 s9, v77
	v_lshrrev_b32_e32 v78, 3, v76
	v_and_b32_e32 v79, 7, v76
	v_lshrrev_b32_e32 v80, 1, v78
	s_and_b32 s4, s9, 1
	s_lshl_b32 s4, s4, 2
	v_or_b32_e32 v80, s4, v80
	v_xor_b32_e32 v79, v79, v80
	s_lshl_b32 s4, s9, 3
	v_add_u32_e32 v78, s4, v78
	v_lshlrev_b32_e32 v78, 11, v78
	v_lshl_add_u32 v56, v79, 4, v78
	v_add_u32_e32 v57, 0x10000, v56
	v_add_u32_e32 v58, 0x20000, v56
	v_add_u32_e32 v59, 0x30000, v56
	s_lshl_b32 s4, s22, 18
	s_add_u32 s0, s48, s4
	s_addc_u32 s1, s49, 0
	s_lshl_b32 s4, s64, 18
	s_add_u32 s2, s44, s4
	s_addc_u32 s3, s45, 0
	s_lshl_b32 s4, s9, 10
	s_add_u32 s4, s4, 16
	v_bfe_u32 v2, v0, 4, 2
	v_bfe_u32 v81, v0, 1, 3
	v_xor_b32_e32 v82, v2, v81
	v_or_b32_e32 v83, 4, v2
	v_xor_b32_e32 v83, v83, v81
	v_lshlrev_b32_e32 v82, 4, v82
	v_lshlrev_b32_e32 v83, 4, v83
	v_lshlrev_b32_e32 v84, 7, v93
	v_ashrrev_i32_e32 v92, 7, v0
	s_lshr_b32 s9, s9, 1
	s_lshl_b32 s9, s9, 13
	v_add3_u32 v64, v84, s9, 16
	v_add_u32_e32 v65, v64, v83
	v_add_u32_e32 v64, v64, v82
	v_bfe_u32 v85, v0, 6, 1
	s_lshl_b32 s9, s64, 7
	v_lshl_or_b32 v94, v85, 6, s9
	v_lshlrev_b32_e32 v85, 13, v85
	v_add3_u32 v66, v84, v85, 16
	v_add_u32_e32 v66, 0x4000, v66
	v_add_u32_e32 v67, v66, v83
	v_add_u32_e32 v66, v66, v82
	v_mov_b32_e32 v60, 0
	v_mov_b32_e32 v61, 0
	v_mov_b32_e32 v62, 0
	v_mov_b32_e32 v63, 0
	v_mov_b32_e32 v68, 0
	v_mov_b32_e32 v69, 0
	v_mov_b32_e32 v70, 0
	v_mov_b32_e32 v71, 0
	v_mov_b32_e32 v52, 0
	v_mov_b32_e32 v53, 0
	v_mov_b32_e32 v54, 0
	v_mov_b32_e32 v55, 0
	v_mov_b32_e32 v40, 0
	v_mov_b32_e32 v41, 0
	v_mov_b32_e32 v42, 0
	v_mov_b32_e32 v43, 0
	v_mov_b32_e32 v72, 0
	v_mov_b32_e32 v73, 0
	v_mov_b32_e32 v74, 0
	v_mov_b32_e32 v75, 0
	v_mov_b32_e32 v48, 0
	v_mov_b32_e32 v49, 0
	v_mov_b32_e32 v50, 0
	v_mov_b32_e32 v51, 0
	v_mov_b32_e32 v44, 0
	v_mov_b32_e32 v45, 0
	v_mov_b32_e32 v46, 0
	v_mov_b32_e32 v47, 0
	v_mov_b32_e32 v36, 0
	v_mov_b32_e32 v37, 0
	v_mov_b32_e32 v38, 0
	v_mov_b32_e32 v39, 0
	v_mov_b32_e32 v32, 0
	v_mov_b32_e32 v33, 0
	v_mov_b32_e32 v34, 0
	v_mov_b32_e32 v35, 0
	v_mov_b32_e32 v28, 0
	v_mov_b32_e32 v29, 0
	v_mov_b32_e32 v30, 0
	v_mov_b32_e32 v31, 0
	v_mov_b32_e32 v24, 0
	v_mov_b32_e32 v25, 0
	v_mov_b32_e32 v26, 0
	v_mov_b32_e32 v27, 0
	v_mov_b32_e32 v20, 0
	v_mov_b32_e32 v21, 0
	v_mov_b32_e32 v22, 0
	v_mov_b32_e32 v23, 0
	v_mov_b32_e32 v16, 0
	v_mov_b32_e32 v17, 0
	v_mov_b32_e32 v18, 0
	v_mov_b32_e32 v19, 0
	v_mov_b32_e32 v12, 0
	v_mov_b32_e32 v13, 0
	v_mov_b32_e32 v14, 0
	v_mov_b32_e32 v15, 0
	v_mov_b32_e32 v8, 0
	v_mov_b32_e32 v9, 0
	v_mov_b32_e32 v10, 0
	v_mov_b32_e32 v11, 0
	v_mov_b32_e32 v4, 0
	v_mov_b32_e32 v5, 0
	v_mov_b32_e32 v6, 0
	v_mov_b32_e32 v7, 0
	s_add_u32 m0, s4, 0x0
	s_nop 0
	global_load_lds_dwordx4 v56, s[0:1]
	s_add_u32 m0, s4, 0x1000
	s_nop 0
	global_load_lds_dwordx4 v57, s[0:1]
	s_add_u32 m0, s4, 0x2000
	s_nop 0
	global_load_lds_dwordx4 v58, s[0:1]
	s_add_u32 m0, s4, 0x3000
	s_nop 0
	global_load_lds_dwordx4 v59, s[0:1]
	s_add_u32 m0, s4, 0x4000
	s_nop 0
	global_load_lds_dwordx4 v56, s[2:3]
	s_add_u32 m0, s4, 0x5000
	s_nop 0
	global_load_lds_dwordx4 v57, s[2:3]
	s_add_u32 m0, s4, 0x6000
	s_nop 0
	global_load_lds_dwordx4 v58, s[2:3]
	s_add_u32 m0, s4, 0x7000
	s_nop 0
	global_load_lds_dwordx4 v59, s[2:3]
	s_add_u32 s0, s0, 0x80
	s_addc_u32 s1, s1, 0
	s_add_u32 s2, s2, 0x80
	s_addc_u32 s3, s3, 0
	s_waitcnt vmcnt(0)
	s_barrier
	ds_read_b128 v[140:143], v66 offset:0
	ds_read_b128 v[144:147], v66 offset:2048
	ds_read_b128 v[148:151], v66 offset:4096
	ds_read_b128 v[152:155], v66 offset:6144
	ds_read_b128 v[156:159], v64 offset:0
	ds_read_b128 v[160:163], v64 offset:2048
	ds_read_b128 v[164:167], v64 offset:4096
	ds_read_b128 v[168:171], v64 offset:6144
	s_waitcnt lgkmcnt(0)
	ds_read_b128 v[172:175], v67 offset:0
	ds_read_b128 v[176:179], v67 offset:2048
	ds_read_b128 v[180:183], v67 offset:4096
	ds_read_b128 v[184:187], v67 offset:6144
	ds_read_b128 v[188:191], v65 offset:0
	ds_read_b128 v[192:195], v65 offset:2048
	ds_read_b128 v[196:199], v65 offset:4096
	ds_read_b128 v[200:203], v65 offset:6144
	v_mfma_f32_16x16x32_bf16 v[60:63], v[140:143], v[156:159], v[60:63]
	v_mfma_f32_16x16x32_bf16 v[68:71], v[140:143], v[160:163], v[68:71]
	s_add_u32 m0, s4, 0x8000
	s_nop 0
	global_load_lds_dwordx4 v56, s[0:1]
	v_mfma_f32_16x16x32_bf16 v[52:55], v[140:143], v[164:167], v[52:55]
	v_mfma_f32_16x16x32_bf16 v[40:43], v[140:143], v[168:171], v[40:43]
	s_add_u32 m0, s4, 0x9000
	s_nop 0
	global_load_lds_dwordx4 v57, s[0:1]
	v_mfma_f32_16x16x32_bf16 v[72:75], v[144:147], v[156:159], v[72:75]
	v_mfma_f32_16x16x32_bf16 v[48:51], v[144:147], v[160:163], v[48:51]
	s_add_u32 m0, s4, 0xa000
	s_nop 0
	global_load_lds_dwordx4 v58, s[0:1]
	v_mfma_f32_16x16x32_bf16 v[44:47], v[144:147], v[164:167], v[44:47]
	v_mfma_f32_16x16x32_bf16 v[36:39], v[144:147], v[168:171], v[36:39]
	s_add_u32 m0, s4, 0xb000
	s_nop 0
	global_load_lds_dwordx4 v59, s[0:1]
	v_mfma_f32_16x16x32_bf16 v[32:35], v[148:151], v[156:159], v[32:35]
	v_mfma_f32_16x16x32_bf16 v[28:31], v[148:151], v[160:163], v[28:31]
	s_add_u32 m0, s4, 0xc000
	s_nop 0
	global_load_lds_dwordx4 v56, s[2:3]
	v_mfma_f32_16x16x32_bf16 v[24:27], v[148:151], v[164:167], v[24:27]
	v_mfma_f32_16x16x32_bf16 v[20:23], v[148:151], v[168:171], v[20:23]
	s_add_u32 m0, s4, 0xd000
	s_nop 0
	global_load_lds_dwordx4 v57, s[2:3]
	v_mfma_f32_16x16x32_bf16 v[16:19], v[152:155], v[156:159], v[16:19]
	v_mfma_f32_16x16x32_bf16 v[12:15], v[152:155], v[160:163], v[12:15]
	s_add_u32 m0, s4, 0xe000
	s_nop 0
	global_load_lds_dwordx4 v58, s[2:3]
	v_mfma_f32_16x16x32_bf16 v[8:11], v[152:155], v[164:167], v[8:11]
	v_mfma_f32_16x16x32_bf16 v[4:7], v[152:155], v[168:171], v[4:7]
	s_add_u32 m0, s4, 0xf000
	s_nop 0
	global_load_lds_dwordx4 v59, s[2:3]
	s_add_u32 s0, s0, 0x80
	s_addc_u32 s1, s1, 0
	s_add_u32 s2, s2, 0x80
	s_addc_u32 s3, s3, 0
	s_waitcnt vmcnt(0) lgkmcnt(0)
	s_barrier
	ds_read_b128 v[140:143], v66 offset:32768
	ds_read_b128 v[144:147], v66 offset:34816
	ds_read_b128 v[148:151], v66 offset:36864
	ds_read_b128 v[152:155], v66 offset:38912
	ds_read_b128 v[156:159], v64 offset:32768
	ds_read_b128 v[160:163], v64 offset:34816
	ds_read_b128 v[164:167], v64 offset:36864
	ds_read_b128 v[168:171], v64 offset:38912
	v_mfma_f32_16x16x32_bf16 v[60:63], v[172:175], v[188:191], v[60:63]
	v_mfma_f32_16x16x32_bf16 v[68:71], v[172:175], v[192:195], v[68:71]
	v_mfma_f32_16x16x32_bf16 v[52:55], v[172:175], v[196:199], v[52:55]
	v_mfma_f32_16x16x32_bf16 v[40:43], v[172:175], v[200:203], v[40:43]
	v_mfma_f32_16x16x32_bf16 v[72:75], v[176:179], v[188:191], v[72:75]
	v_mfma_f32_16x16x32_bf16 v[48:51], v[176:179], v[192:195], v[48:51]
	v_mfma_f32_16x16x32_bf16 v[44:47], v[176:179], v[196:199], v[44:47]
	v_mfma_f32_16x16x32_bf16 v[36:39], v[176:179], v[200:203], v[36:39]
	v_mfma_f32_16x16x32_bf16 v[32:35], v[180:183], v[188:191], v[32:35]
	v_mfma_f32_16x16x32_bf16 v[28:31], v[180:183], v[192:195], v[28:31]
	v_mfma_f32_16x16x32_bf16 v[24:27], v[180:183], v[196:199], v[24:27]
	v_mfma_f32_16x16x32_bf16 v[20:23], v[180:183], v[200:203], v[20:23]
	v_mfma_f32_16x16x32_bf16 v[16:19], v[184:187], v[188:191], v[16:19]
	v_mfma_f32_16x16x32_bf16 v[12:15], v[184:187], v[192:195], v[12:15]
	v_mfma_f32_16x16x32_bf16 v[8:11], v[184:187], v[196:199], v[8:11]
	v_mfma_f32_16x16x32_bf16 v[4:7], v[184:187], v[200:203], v[4:7]
	s_waitcnt lgkmcnt(0)
	ds_read_b128 v[172:175], v67 offset:32768
	ds_read_b128 v[176:179], v67 offset:34816
	ds_read_b128 v[180:183], v67 offset:36864
	ds_read_b128 v[184:187], v67 offset:38912
	ds_read_b128 v[188:191], v65 offset:32768
	ds_read_b128 v[192:195], v65 offset:34816
	ds_read_b128 v[196:199], v65 offset:36864
	ds_read_b128 v[200:203], v65 offset:38912
	v_mfma_f32_16x16x32_bf16 v[60:63], v[140:143], v[156:159], v[60:63]
	v_mfma_f32_16x16x32_bf16 v[68:71], v[140:143], v[160:163], v[68:71]
	s_add_u32 m0, s4, 0x0
	s_nop 0
	global_load_lds_dwordx4 v56, s[0:1]
	v_mfma_f32_16x16x32_bf16 v[52:55], v[140:143], v[164:167], v[52:55]
	v_mfma_f32_16x16x32_bf16 v[40:43], v[140:143], v[168:171], v[40:43]
	s_add_u32 m0, s4, 0x1000
	s_nop 0
	global_load_lds_dwordx4 v57, s[0:1]
	v_mfma_f32_16x16x32_bf16 v[72:75], v[144:147], v[156:159], v[72:75]
	v_mfma_f32_16x16x32_bf16 v[48:51], v[144:147], v[160:163], v[48:51]
	s_add_u32 m0, s4, 0x2000
	s_nop 0
	global_load_lds_dwordx4 v58, s[0:1]
	v_mfma_f32_16x16x32_bf16 v[44:47], v[144:147], v[164:167], v[44:47]
	v_mfma_f32_16x16x32_bf16 v[36:39], v[144:147], v[168:171], v[36:39]
	s_add_u32 m0, s4, 0x3000
	s_nop 0
	global_load_lds_dwordx4 v59, s[0:1]
	v_mfma_f32_16x16x32_bf16 v[32:35], v[148:151], v[156:159], v[32:35]
	v_mfma_f32_16x16x32_bf16 v[28:31], v[148:151], v[160:163], v[28:31]
	s_add_u32 m0, s4, 0x4000
	s_nop 0
	global_load_lds_dwordx4 v56, s[2:3]
	v_mfma_f32_16x16x32_bf16 v[24:27], v[148:151], v[164:167], v[24:27]
	v_mfma_f32_16x16x32_bf16 v[20:23], v[148:151], v[168:171], v[20:23]
	s_add_u32 m0, s4, 0x5000
	s_nop 0
	global_load_lds_dwordx4 v57, s[2:3]
	v_mfma_f32_16x16x32_bf16 v[16:19], v[152:155], v[156:159], v[16:19]
	v_mfma_f32_16x16x32_bf16 v[12:15], v[152:155], v[160:163], v[12:15]
	s_add_u32 m0, s4, 0x6000
	s_nop 0
	global_load_lds_dwordx4 v58, s[2:3]
	v_mfma_f32_16x16x32_bf16 v[8:11], v[152:155], v[164:167], v[8:11]
	v_mfma_f32_16x16x32_bf16 v[4:7], v[152:155], v[168:171], v[4:7]
	s_add_u32 m0, s4, 0x7000
	s_nop 0
	global_load_lds_dwordx4 v59, s[2:3]
	s_add_u32 s0, s0, 0x80
	s_addc_u32 s1, s1, 0
	s_add_u32 s2, s2, 0x80
	s_addc_u32 s3, s3, 0
	s_waitcnt vmcnt(0) lgkmcnt(0)
	s_barrier
	ds_read_b128 v[140:143], v66 offset:0
	ds_read_b128 v[144:147], v66 offset:2048
	ds_read_b128 v[148:151], v66 offset:4096
	ds_read_b128 v[152:155], v66 offset:6144
	ds_read_b128 v[156:159], v64 offset:0
	ds_read_b128 v[160:163], v64 offset:2048
	ds_read_b128 v[164:167], v64 offset:4096
	ds_read_b128 v[168:171], v64 offset:6144
	v_mfma_f32_16x16x32_bf16 v[60:63], v[172:175], v[188:191], v[60:63]
	v_mfma_f32_16x16x32_bf16 v[68:71], v[172:175], v[192:195], v[68:71]
	v_mfma_f32_16x16x32_bf16 v[52:55], v[172:175], v[196:199], v[52:55]
	v_mfma_f32_16x16x32_bf16 v[40:43], v[172:175], v[200:203], v[40:43]
	v_mfma_f32_16x16x32_bf16 v[72:75], v[176:179], v[188:191], v[72:75]
	v_mfma_f32_16x16x32_bf16 v[48:51], v[176:179], v[192:195], v[48:51]
	v_mfma_f32_16x16x32_bf16 v[44:47], v[176:179], v[196:199], v[44:47]
	v_mfma_f32_16x16x32_bf16 v[36:39], v[176:179], v[200:203], v[36:39]
	v_mfma_f32_16x16x32_bf16 v[32:35], v[180:183], v[188:191], v[32:35]
	v_mfma_f32_16x16x32_bf16 v[28:31], v[180:183], v[192:195], v[28:31]
	v_mfma_f32_16x16x32_bf16 v[24:27], v[180:183], v[196:199], v[24:27]
	v_mfma_f32_16x16x32_bf16 v[20:23], v[180:183], v[200:203], v[20:23]
	v_mfma_f32_16x16x32_bf16 v[16:19], v[184:187], v[188:191], v[16:19]
	v_mfma_f32_16x16x32_bf16 v[12:15], v[184:187], v[192:195], v[12:15]
	v_mfma_f32_16x16x32_bf16 v[8:11], v[184:187], v[196:199], v[8:11]
	v_mfma_f32_16x16x32_bf16 v[4:7], v[184:187], v[200:203], v[4:7]
	s_waitcnt lgkmcnt(0)
	ds_read_b128 v[172:175], v67 offset:0
	ds_read_b128 v[176:179], v67 offset:2048
	ds_read_b128 v[180:183], v67 offset:4096
	ds_read_b128 v[184:187], v67 offset:6144
	ds_read_b128 v[188:191], v65 offset:0
	ds_read_b128 v[192:195], v65 offset:2048
	ds_read_b128 v[196:199], v65 offset:4096
	ds_read_b128 v[200:203], v65 offset:6144
	v_mfma_f32_16x16x32_bf16 v[60:63], v[140:143], v[156:159], v[60:63]
	v_mfma_f32_16x16x32_bf16 v[68:71], v[140:143], v[160:163], v[68:71]
	s_add_u32 m0, s4, 0x8000
	s_nop 0
	global_load_lds_dwordx4 v56, s[0:1]
	v_mfma_f32_16x16x32_bf16 v[52:55], v[140:143], v[164:167], v[52:55]
	v_mfma_f32_16x16x32_bf16 v[40:43], v[140:143], v[168:171], v[40:43]
	s_add_u32 m0, s4, 0x9000
	s_nop 0
	global_load_lds_dwordx4 v57, s[0:1]
	v_mfma_f32_16x16x32_bf16 v[72:75], v[144:147], v[156:159], v[72:75]
	v_mfma_f32_16x16x32_bf16 v[48:51], v[144:147], v[160:163], v[48:51]
	s_add_u32 m0, s4, 0xa000
	s_nop 0
	global_load_lds_dwordx4 v58, s[0:1]
	v_mfma_f32_16x16x32_bf16 v[44:47], v[144:147], v[164:167], v[44:47]
	v_mfma_f32_16x16x32_bf16 v[36:39], v[144:147], v[168:171], v[36:39]
	s_add_u32 m0, s4, 0xb000
	s_nop 0
	global_load_lds_dwordx4 v59, s[0:1]
	v_mfma_f32_16x16x32_bf16 v[32:35], v[148:151], v[156:159], v[32:35]
	v_mfma_f32_16x16x32_bf16 v[28:31], v[148:151], v[160:163], v[28:31]
	s_add_u32 m0, s4, 0xc000
	s_nop 0
	global_load_lds_dwordx4 v56, s[2:3]
	v_mfma_f32_16x16x32_bf16 v[24:27], v[148:151], v[164:167], v[24:27]
	v_mfma_f32_16x16x32_bf16 v[20:23], v[148:151], v[168:171], v[20:23]
	s_add_u32 m0, s4, 0xd000
	s_nop 0
	global_load_lds_dwordx4 v57, s[2:3]
	v_mfma_f32_16x16x32_bf16 v[16:19], v[152:155], v[156:159], v[16:19]
	v_mfma_f32_16x16x32_bf16 v[12:15], v[152:155], v[160:163], v[12:15]
	s_add_u32 m0, s4, 0xe000
	s_nop 0
	global_load_lds_dwordx4 v58, s[2:3]
	v_mfma_f32_16x16x32_bf16 v[8:11], v[152:155], v[164:167], v[8:11]
	v_mfma_f32_16x16x32_bf16 v[4:7], v[152:155], v[168:171], v[4:7]
	s_add_u32 m0, s4, 0xf000
	s_nop 0
	global_load_lds_dwordx4 v59, s[2:3]
	s_add_u32 s0, s0, 0x80
	s_addc_u32 s1, s1, 0
	s_add_u32 s2, s2, 0x80
	s_addc_u32 s3, s3, 0
	s_waitcnt vmcnt(0) lgkmcnt(0)
	s_barrier
	ds_read_b128 v[140:143], v66 offset:32768
	ds_read_b128 v[144:147], v66 offset:34816
	ds_read_b128 v[148:151], v66 offset:36864
	ds_read_b128 v[152:155], v66 offset:38912
	ds_read_b128 v[156:159], v64 offset:32768
	ds_read_b128 v[160:163], v64 offset:34816
	ds_read_b128 v[164:167], v64 offset:36864
	ds_read_b128 v[168:171], v64 offset:38912
	v_mfma_f32_16x16x32_bf16 v[60:63], v[172:175], v[188:191], v[60:63]
	v_mfma_f32_16x16x32_bf16 v[68:71], v[172:175], v[192:195], v[68:71]
	v_mfma_f32_16x16x32_bf16 v[52:55], v[172:175], v[196:199], v[52:55]
	v_mfma_f32_16x16x32_bf16 v[40:43], v[172:175], v[200:203], v[40:43]
	v_mfma_f32_16x16x32_bf16 v[72:75], v[176:179], v[188:191], v[72:75]
	v_mfma_f32_16x16x32_bf16 v[48:51], v[176:179], v[192:195], v[48:51]
	v_mfma_f32_16x16x32_bf16 v[44:47], v[176:179], v[196:199], v[44:47]
	v_mfma_f32_16x16x32_bf16 v[36:39], v[176:179], v[200:203], v[36:39]
	v_mfma_f32_16x16x32_bf16 v[32:35], v[180:183], v[188:191], v[32:35]
	v_mfma_f32_16x16x32_bf16 v[28:31], v[180:183], v[192:195], v[28:31]
	v_mfma_f32_16x16x32_bf16 v[24:27], v[180:183], v[196:199], v[24:27]
	v_mfma_f32_16x16x32_bf16 v[20:23], v[180:183], v[200:203], v[20:23]
	v_mfma_f32_16x16x32_bf16 v[16:19], v[184:187], v[188:191], v[16:19]
	v_mfma_f32_16x16x32_bf16 v[12:15], v[184:187], v[192:195], v[12:15]
	v_mfma_f32_16x16x32_bf16 v[8:11], v[184:187], v[196:199], v[8:11]
	v_mfma_f32_16x16x32_bf16 v[4:7], v[184:187], v[200:203], v[4:7]
	s_waitcnt lgkmcnt(0)
	ds_read_b128 v[172:175], v67 offset:32768
	ds_read_b128 v[176:179], v67 offset:34816
	ds_read_b128 v[180:183], v67 offset:36864
	ds_read_b128 v[184:187], v67 offset:38912
	ds_read_b128 v[188:191], v65 offset:32768
	ds_read_b128 v[192:195], v65 offset:34816
	ds_read_b128 v[196:199], v65 offset:36864
	ds_read_b128 v[200:203], v65 offset:38912
	v_mfma_f32_16x16x32_bf16 v[60:63], v[140:143], v[156:159], v[60:63]
	v_mfma_f32_16x16x32_bf16 v[68:71], v[140:143], v[160:163], v[68:71]
	s_add_u32 m0, s4, 0x0
	s_nop 0
	global_load_lds_dwordx4 v56, s[0:1]
	v_mfma_f32_16x16x32_bf16 v[52:55], v[140:143], v[164:167], v[52:55]
	v_mfma_f32_16x16x32_bf16 v[40:43], v[140:143], v[168:171], v[40:43]
	s_add_u32 m0, s4, 0x1000
	s_nop 0
	global_load_lds_dwordx4 v57, s[0:1]
	v_mfma_f32_16x16x32_bf16 v[72:75], v[144:147], v[156:159], v[72:75]
	v_mfma_f32_16x16x32_bf16 v[48:51], v[144:147], v[160:163], v[48:51]
	s_add_u32 m0, s4, 0x2000
	s_nop 0
	global_load_lds_dwordx4 v58, s[0:1]
	v_mfma_f32_16x16x32_bf16 v[44:47], v[144:147], v[164:167], v[44:47]
	v_mfma_f32_16x16x32_bf16 v[36:39], v[144:147], v[168:171], v[36:39]
	s_add_u32 m0, s4, 0x3000
	s_nop 0
	global_load_lds_dwordx4 v59, s[0:1]
	v_mfma_f32_16x16x32_bf16 v[32:35], v[148:151], v[156:159], v[32:35]
	v_mfma_f32_16x16x32_bf16 v[28:31], v[148:151], v[160:163], v[28:31]
	s_add_u32 m0, s4, 0x4000
	s_nop 0
	global_load_lds_dwordx4 v56, s[2:3]
	v_mfma_f32_16x16x32_bf16 v[24:27], v[148:151], v[164:167], v[24:27]
	v_mfma_f32_16x16x32_bf16 v[20:23], v[148:151], v[168:171], v[20:23]
	s_add_u32 m0, s4, 0x5000
	s_nop 0
	global_load_lds_dwordx4 v57, s[2:3]
	v_mfma_f32_16x16x32_bf16 v[16:19], v[152:155], v[156:159], v[16:19]
	v_mfma_f32_16x16x32_bf16 v[12:15], v[152:155], v[160:163], v[12:15]
	s_add_u32 m0, s4, 0x6000
	s_nop 0
	global_load_lds_dwordx4 v58, s[2:3]
	v_mfma_f32_16x16x32_bf16 v[8:11], v[152:155], v[164:167], v[8:11]
	v_mfma_f32_16x16x32_bf16 v[4:7], v[152:155], v[168:171], v[4:7]
	s_add_u32 m0, s4, 0x7000
	s_nop 0
	global_load_lds_dwordx4 v59, s[2:3]
	s_add_u32 s0, s0, 0x80
	s_addc_u32 s1, s1, 0
	s_add_u32 s2, s2, 0x80
	s_addc_u32 s3, s3, 0
	s_waitcnt vmcnt(0) lgkmcnt(0)
	s_barrier
	ds_read_b128 v[140:143], v66 offset:0
	ds_read_b128 v[144:147], v66 offset:2048
	ds_read_b128 v[148:151], v66 offset:4096
	ds_read_b128 v[152:155], v66 offset:6144
	ds_read_b128 v[156:159], v64 offset:0
	ds_read_b128 v[160:163], v64 offset:2048
	ds_read_b128 v[164:167], v64 offset:4096
	ds_read_b128 v[168:171], v64 offset:6144
	v_mfma_f32_16x16x32_bf16 v[60:63], v[172:175], v[188:191], v[60:63]
	v_mfma_f32_16x16x32_bf16 v[68:71], v[172:175], v[192:195], v[68:71]
	v_mfma_f32_16x16x32_bf16 v[52:55], v[172:175], v[196:199], v[52:55]
	v_mfma_f32_16x16x32_bf16 v[40:43], v[172:175], v[200:203], v[40:43]
	v_mfma_f32_16x16x32_bf16 v[72:75], v[176:179], v[188:191], v[72:75]
	v_mfma_f32_16x16x32_bf16 v[48:51], v[176:179], v[192:195], v[48:51]
	v_mfma_f32_16x16x32_bf16 v[44:47], v[176:179], v[196:199], v[44:47]
	v_mfma_f32_16x16x32_bf16 v[36:39], v[176:179], v[200:203], v[36:39]
	v_mfma_f32_16x16x32_bf16 v[32:35], v[180:183], v[188:191], v[32:35]
	v_mfma_f32_16x16x32_bf16 v[28:31], v[180:183], v[192:195], v[28:31]
	v_mfma_f32_16x16x32_bf16 v[24:27], v[180:183], v[196:199], v[24:27]
	v_mfma_f32_16x16x32_bf16 v[20:23], v[180:183], v[200:203], v[20:23]
	v_mfma_f32_16x16x32_bf16 v[16:19], v[184:187], v[188:191], v[16:19]
	v_mfma_f32_16x16x32_bf16 v[12:15], v[184:187], v[192:195], v[12:15]
	v_mfma_f32_16x16x32_bf16 v[8:11], v[184:187], v[196:199], v[8:11]
	v_mfma_f32_16x16x32_bf16 v[4:7], v[184:187], v[200:203], v[4:7]
	s_waitcnt lgkmcnt(0)
	ds_read_b128 v[172:175], v67 offset:0
	ds_read_b128 v[176:179], v67 offset:2048
	ds_read_b128 v[180:183], v67 offset:4096
	ds_read_b128 v[184:187], v67 offset:6144
	ds_read_b128 v[188:191], v65 offset:0
	ds_read_b128 v[192:195], v65 offset:2048
	ds_read_b128 v[196:199], v65 offset:4096
	ds_read_b128 v[200:203], v65 offset:6144
	v_mfma_f32_16x16x32_bf16 v[60:63], v[140:143], v[156:159], v[60:63]
	v_mfma_f32_16x16x32_bf16 v[68:71], v[140:143], v[160:163], v[68:71]
	s_add_u32 m0, s4, 0x8000
	s_nop 0
	global_load_lds_dwordx4 v56, s[0:1]
	v_mfma_f32_16x16x32_bf16 v[52:55], v[140:143], v[164:167], v[52:55]
	v_mfma_f32_16x16x32_bf16 v[40:43], v[140:143], v[168:171], v[40:43]
	s_add_u32 m0, s4, 0x9000
	s_nop 0
	global_load_lds_dwordx4 v57, s[0:1]
	v_mfma_f32_16x16x32_bf16 v[72:75], v[144:147], v[156:159], v[72:75]
	v_mfma_f32_16x16x32_bf16 v[48:51], v[144:147], v[160:163], v[48:51]
	s_add_u32 m0, s4, 0xa000
	s_nop 0
	global_load_lds_dwordx4 v58, s[0:1]
	v_mfma_f32_16x16x32_bf16 v[44:47], v[144:147], v[164:167], v[44:47]
	v_mfma_f32_16x16x32_bf16 v[36:39], v[144:147], v[168:171], v[36:39]
	s_add_u32 m0, s4, 0xb000
	s_nop 0
	global_load_lds_dwordx4 v59, s[0:1]
	v_mfma_f32_16x16x32_bf16 v[32:35], v[148:151], v[156:159], v[32:35]
	v_mfma_f32_16x16x32_bf16 v[28:31], v[148:151], v[160:163], v[28:31]
	s_add_u32 m0, s4, 0xc000
	s_nop 0
	global_load_lds_dwordx4 v56, s[2:3]
	v_mfma_f32_16x16x32_bf16 v[24:27], v[148:151], v[164:167], v[24:27]
	v_mfma_f32_16x16x32_bf16 v[20:23], v[148:151], v[168:171], v[20:23]
	s_add_u32 m0, s4, 0xd000
	s_nop 0
	global_load_lds_dwordx4 v57, s[2:3]
	v_mfma_f32_16x16x32_bf16 v[16:19], v[152:155], v[156:159], v[16:19]
	v_mfma_f32_16x16x32_bf16 v[12:15], v[152:155], v[160:163], v[12:15]
	s_add_u32 m0, s4, 0xe000
	s_nop 0
	global_load_lds_dwordx4 v58, s[2:3]
	v_mfma_f32_16x16x32_bf16 v[8:11], v[152:155], v[164:167], v[8:11]
	v_mfma_f32_16x16x32_bf16 v[4:7], v[152:155], v[168:171], v[4:7]
	s_add_u32 m0, s4, 0xf000
	s_nop 0
	global_load_lds_dwordx4 v59, s[2:3]
	s_add_u32 s0, s0, 0x80
	s_addc_u32 s1, s1, 0
	s_add_u32 s2, s2, 0x80
	s_addc_u32 s3, s3, 0
	s_waitcnt vmcnt(0) lgkmcnt(0)
	s_barrier
	ds_read_b128 v[140:143], v66 offset:32768
	ds_read_b128 v[144:147], v66 offset:34816
	ds_read_b128 v[148:151], v66 offset:36864
	ds_read_b128 v[152:155], v66 offset:38912
	ds_read_b128 v[156:159], v64 offset:32768
	ds_read_b128 v[160:163], v64 offset:34816
	ds_read_b128 v[164:167], v64 offset:36864
	ds_read_b128 v[168:171], v64 offset:38912
	v_mfma_f32_16x16x32_bf16 v[60:63], v[172:175], v[188:191], v[60:63]
	v_mfma_f32_16x16x32_bf16 v[68:71], v[172:175], v[192:195], v[68:71]
	v_mfma_f32_16x16x32_bf16 v[52:55], v[172:175], v[196:199], v[52:55]
	v_mfma_f32_16x16x32_bf16 v[40:43], v[172:175], v[200:203], v[40:43]
	v_mfma_f32_16x16x32_bf16 v[72:75], v[176:179], v[188:191], v[72:75]
	v_mfma_f32_16x16x32_bf16 v[48:51], v[176:179], v[192:195], v[48:51]
	v_mfma_f32_16x16x32_bf16 v[44:47], v[176:179], v[196:199], v[44:47]
	v_mfma_f32_16x16x32_bf16 v[36:39], v[176:179], v[200:203], v[36:39]
	v_mfma_f32_16x16x32_bf16 v[32:35], v[180:183], v[188:191], v[32:35]
	v_mfma_f32_16x16x32_bf16 v[28:31], v[180:183], v[192:195], v[28:31]
	v_mfma_f32_16x16x32_bf16 v[24:27], v[180:183], v[196:199], v[24:27]
	v_mfma_f32_16x16x32_bf16 v[20:23], v[180:183], v[200:203], v[20:23]
	v_mfma_f32_16x16x32_bf16 v[16:19], v[184:187], v[188:191], v[16:19]
	v_mfma_f32_16x16x32_bf16 v[12:15], v[184:187], v[192:195], v[12:15]
	v_mfma_f32_16x16x32_bf16 v[8:11], v[184:187], v[196:199], v[8:11]
	v_mfma_f32_16x16x32_bf16 v[4:7], v[184:187], v[200:203], v[4:7]
	s_waitcnt lgkmcnt(0)
	ds_read_b128 v[172:175], v67 offset:32768
	ds_read_b128 v[176:179], v67 offset:34816
	ds_read_b128 v[180:183], v67 offset:36864
	ds_read_b128 v[184:187], v67 offset:38912
	ds_read_b128 v[188:191], v65 offset:32768
	ds_read_b128 v[192:195], v65 offset:34816
	ds_read_b128 v[196:199], v65 offset:36864
	ds_read_b128 v[200:203], v65 offset:38912
	v_mfma_f32_16x16x32_bf16 v[60:63], v[140:143], v[156:159], v[60:63]
	v_mfma_f32_16x16x32_bf16 v[68:71], v[140:143], v[160:163], v[68:71]
	s_add_u32 m0, s4, 0x0
	s_nop 0
	global_load_lds_dwordx4 v56, s[0:1]
	v_mfma_f32_16x16x32_bf16 v[52:55], v[140:143], v[164:167], v[52:55]
	v_mfma_f32_16x16x32_bf16 v[40:43], v[140:143], v[168:171], v[40:43]
	s_add_u32 m0, s4, 0x1000
	s_nop 0
	global_load_lds_dwordx4 v57, s[0:1]
	v_mfma_f32_16x16x32_bf16 v[72:75], v[144:147], v[156:159], v[72:75]
	v_mfma_f32_16x16x32_bf16 v[48:51], v[144:147], v[160:163], v[48:51]
	s_add_u32 m0, s4, 0x2000
	s_nop 0
	global_load_lds_dwordx4 v58, s[0:1]
	v_mfma_f32_16x16x32_bf16 v[44:47], v[144:147], v[164:167], v[44:47]
	v_mfma_f32_16x16x32_bf16 v[36:39], v[144:147], v[168:171], v[36:39]
	s_add_u32 m0, s4, 0x3000
	s_nop 0
	global_load_lds_dwordx4 v59, s[0:1]
	v_mfma_f32_16x16x32_bf16 v[32:35], v[148:151], v[156:159], v[32:35]
	v_mfma_f32_16x16x32_bf16 v[28:31], v[148:151], v[160:163], v[28:31]
	s_add_u32 m0, s4, 0x4000
	s_nop 0
	global_load_lds_dwordx4 v56, s[2:3]
	v_mfma_f32_16x16x32_bf16 v[24:27], v[148:151], v[164:167], v[24:27]
	v_mfma_f32_16x16x32_bf16 v[20:23], v[148:151], v[168:171], v[20:23]
	s_add_u32 m0, s4, 0x5000
	s_nop 0
	global_load_lds_dwordx4 v57, s[2:3]
	v_mfma_f32_16x16x32_bf16 v[16:19], v[152:155], v[156:159], v[16:19]
	v_mfma_f32_16x16x32_bf16 v[12:15], v[152:155], v[160:163], v[12:15]
	s_add_u32 m0, s4, 0x6000
	s_nop 0
	global_load_lds_dwordx4 v58, s[2:3]
	v_mfma_f32_16x16x32_bf16 v[8:11], v[152:155], v[164:167], v[8:11]
	v_mfma_f32_16x16x32_bf16 v[4:7], v[152:155], v[168:171], v[4:7]
	s_add_u32 m0, s4, 0x7000
	s_nop 0
	global_load_lds_dwordx4 v59, s[2:3]
	s_add_u32 s0, s0, 0x80
	s_addc_u32 s1, s1, 0
	s_add_u32 s2, s2, 0x80
	s_addc_u32 s3, s3, 0
	s_waitcnt vmcnt(0) lgkmcnt(0)
	s_barrier
	ds_read_b128 v[140:143], v66 offset:0
	ds_read_b128 v[144:147], v66 offset:2048
	ds_read_b128 v[148:151], v66 offset:4096
	ds_read_b128 v[152:155], v66 offset:6144
	ds_read_b128 v[156:159], v64 offset:0
	ds_read_b128 v[160:163], v64 offset:2048
	ds_read_b128 v[164:167], v64 offset:4096
	ds_read_b128 v[168:171], v64 offset:6144
	v_mfma_f32_16x16x32_bf16 v[60:63], v[172:175], v[188:191], v[60:63]
	v_mfma_f32_16x16x32_bf16 v[68:71], v[172:175], v[192:195], v[68:71]
	v_mfma_f32_16x16x32_bf16 v[52:55], v[172:175], v[196:199], v[52:55]
	v_mfma_f32_16x16x32_bf16 v[40:43], v[172:175], v[200:203], v[40:43]
	v_mfma_f32_16x16x32_bf16 v[72:75], v[176:179], v[188:191], v[72:75]
	v_mfma_f32_16x16x32_bf16 v[48:51], v[176:179], v[192:195], v[48:51]
	v_mfma_f32_16x16x32_bf16 v[44:47], v[176:179], v[196:199], v[44:47]
	v_mfma_f32_16x16x32_bf16 v[36:39], v[176:179], v[200:203], v[36:39]
	v_mfma_f32_16x16x32_bf16 v[32:35], v[180:183], v[188:191], v[32:35]
	v_mfma_f32_16x16x32_bf16 v[28:31], v[180:183], v[192:195], v[28:31]
	v_mfma_f32_16x16x32_bf16 v[24:27], v[180:183], v[196:199], v[24:27]
	v_mfma_f32_16x16x32_bf16 v[20:23], v[180:183], v[200:203], v[20:23]
	v_mfma_f32_16x16x32_bf16 v[16:19], v[184:187], v[188:191], v[16:19]
	v_mfma_f32_16x16x32_bf16 v[12:15], v[184:187], v[192:195], v[12:15]
	v_mfma_f32_16x16x32_bf16 v[8:11], v[184:187], v[196:199], v[8:11]
	v_mfma_f32_16x16x32_bf16 v[4:7], v[184:187], v[200:203], v[4:7]
	s_waitcnt lgkmcnt(0)
	ds_read_b128 v[172:175], v67 offset:0
	ds_read_b128 v[176:179], v67 offset:2048
	ds_read_b128 v[180:183], v67 offset:4096
	ds_read_b128 v[184:187], v67 offset:6144
	ds_read_b128 v[188:191], v65 offset:0
	ds_read_b128 v[192:195], v65 offset:2048
	ds_read_b128 v[196:199], v65 offset:4096
	ds_read_b128 v[200:203], v65 offset:6144
	v_mfma_f32_16x16x32_bf16 v[60:63], v[140:143], v[156:159], v[60:63]
	v_mfma_f32_16x16x32_bf16 v[68:71], v[140:143], v[160:163], v[68:71]
	s_add_u32 m0, s4, 0x8000
	s_nop 0
	global_load_lds_dwordx4 v56, s[0:1]
	v_mfma_f32_16x16x32_bf16 v[52:55], v[140:143], v[164:167], v[52:55]
	v_mfma_f32_16x16x32_bf16 v[40:43], v[140:143], v[168:171], v[40:43]
	s_add_u32 m0, s4, 0x9000
	s_nop 0
	global_load_lds_dwordx4 v57, s[0:1]
	v_mfma_f32_16x16x32_bf16 v[72:75], v[144:147], v[156:159], v[72:75]
	v_mfma_f32_16x16x32_bf16 v[48:51], v[144:147], v[160:163], v[48:51]
	s_add_u32 m0, s4, 0xa000
	s_nop 0
	global_load_lds_dwordx4 v58, s[0:1]
	v_mfma_f32_16x16x32_bf16 v[44:47], v[144:147], v[164:167], v[44:47]
	v_mfma_f32_16x16x32_bf16 v[36:39], v[144:147], v[168:171], v[36:39]
	s_add_u32 m0, s4, 0xb000
	s_nop 0
	global_load_lds_dwordx4 v59, s[0:1]
	v_mfma_f32_16x16x32_bf16 v[32:35], v[148:151], v[156:159], v[32:35]
	v_mfma_f32_16x16x32_bf16 v[28:31], v[148:151], v[160:163], v[28:31]
	s_add_u32 m0, s4, 0xc000
	s_nop 0
	global_load_lds_dwordx4 v56, s[2:3]
	v_mfma_f32_16x16x32_bf16 v[24:27], v[148:151], v[164:167], v[24:27]
	v_mfma_f32_16x16x32_bf16 v[20:23], v[148:151], v[168:171], v[20:23]
	s_add_u32 m0, s4, 0xd000
	s_nop 0
	global_load_lds_dwordx4 v57, s[2:3]
	v_mfma_f32_16x16x32_bf16 v[16:19], v[152:155], v[156:159], v[16:19]
	v_mfma_f32_16x16x32_bf16 v[12:15], v[152:155], v[160:163], v[12:15]
	s_add_u32 m0, s4, 0xe000
	s_nop 0
	global_load_lds_dwordx4 v58, s[2:3]
	v_mfma_f32_16x16x32_bf16 v[8:11], v[152:155], v[164:167], v[8:11]
	v_mfma_f32_16x16x32_bf16 v[4:7], v[152:155], v[168:171], v[4:7]
	s_add_u32 m0, s4, 0xf000
	s_nop 0
	global_load_lds_dwordx4 v59, s[2:3]
	s_add_u32 s0, s0, 0x80
	s_addc_u32 s1, s1, 0
	s_add_u32 s2, s2, 0x80
	s_addc_u32 s3, s3, 0
	s_waitcnt vmcnt(0) lgkmcnt(0)
	s_barrier
	ds_read_b128 v[140:143], v66 offset:32768
	ds_read_b128 v[144:147], v66 offset:34816
	ds_read_b128 v[148:151], v66 offset:36864
	ds_read_b128 v[152:155], v66 offset:38912
	ds_read_b128 v[156:159], v64 offset:32768
	ds_read_b128 v[160:163], v64 offset:34816
	ds_read_b128 v[164:167], v64 offset:36864
	ds_read_b128 v[168:171], v64 offset:38912
	v_mfma_f32_16x16x32_bf16 v[60:63], v[172:175], v[188:191], v[60:63]
	v_mfma_f32_16x16x32_bf16 v[68:71], v[172:175], v[192:195], v[68:71]
	v_mfma_f32_16x16x32_bf16 v[52:55], v[172:175], v[196:199], v[52:55]
	v_mfma_f32_16x16x32_bf16 v[40:43], v[172:175], v[200:203], v[40:43]
	v_mfma_f32_16x16x32_bf16 v[72:75], v[176:179], v[188:191], v[72:75]
	v_mfma_f32_16x16x32_bf16 v[48:51], v[176:179], v[192:195], v[48:51]
	v_mfma_f32_16x16x32_bf16 v[44:47], v[176:179], v[196:199], v[44:47]
	v_mfma_f32_16x16x32_bf16 v[36:39], v[176:179], v[200:203], v[36:39]
	v_mfma_f32_16x16x32_bf16 v[32:35], v[180:183], v[188:191], v[32:35]
	v_mfma_f32_16x16x32_bf16 v[28:31], v[180:183], v[192:195], v[28:31]
	v_mfma_f32_16x16x32_bf16 v[24:27], v[180:183], v[196:199], v[24:27]
	v_mfma_f32_16x16x32_bf16 v[20:23], v[180:183], v[200:203], v[20:23]
	v_mfma_f32_16x16x32_bf16 v[16:19], v[184:187], v[188:191], v[16:19]
	v_mfma_f32_16x16x32_bf16 v[12:15], v[184:187], v[192:195], v[12:15]
	v_mfma_f32_16x16x32_bf16 v[8:11], v[184:187], v[196:199], v[8:11]
	v_mfma_f32_16x16x32_bf16 v[4:7], v[184:187], v[200:203], v[4:7]
	s_waitcnt lgkmcnt(0)
	ds_read_b128 v[172:175], v67 offset:32768
	ds_read_b128 v[176:179], v67 offset:34816
	ds_read_b128 v[180:183], v67 offset:36864
	ds_read_b128 v[184:187], v67 offset:38912
	ds_read_b128 v[188:191], v65 offset:32768
	ds_read_b128 v[192:195], v65 offset:34816
	ds_read_b128 v[196:199], v65 offset:36864
	ds_read_b128 v[200:203], v65 offset:38912
	v_mfma_f32_16x16x32_bf16 v[60:63], v[140:143], v[156:159], v[60:63]
	v_mfma_f32_16x16x32_bf16 v[68:71], v[140:143], v[160:163], v[68:71]
	s_add_u32 m0, s4, 0x0
	s_nop 0
	global_load_lds_dwordx4 v56, s[0:1]
	v_mfma_f32_16x16x32_bf16 v[52:55], v[140:143], v[164:167], v[52:55]
	v_mfma_f32_16x16x32_bf16 v[40:43], v[140:143], v[168:171], v[40:43]
	s_add_u32 m0, s4, 0x1000
	s_nop 0
	global_load_lds_dwordx4 v57, s[0:1]
	v_mfma_f32_16x16x32_bf16 v[72:75], v[144:147], v[156:159], v[72:75]
	v_mfma_f32_16x16x32_bf16 v[48:51], v[144:147], v[160:163], v[48:51]
	s_add_u32 m0, s4, 0x2000
	s_nop 0
	global_load_lds_dwordx4 v58, s[0:1]
	v_mfma_f32_16x16x32_bf16 v[44:47], v[144:147], v[164:167], v[44:47]
	v_mfma_f32_16x16x32_bf16 v[36:39], v[144:147], v[168:171], v[36:39]
	s_add_u32 m0, s4, 0x3000
	s_nop 0
	global_load_lds_dwordx4 v59, s[0:1]
	v_mfma_f32_16x16x32_bf16 v[32:35], v[148:151], v[156:159], v[32:35]
	v_mfma_f32_16x16x32_bf16 v[28:31], v[148:151], v[160:163], v[28:31]
	s_add_u32 m0, s4, 0x4000
	s_nop 0
	global_load_lds_dwordx4 v56, s[2:3]
	v_mfma_f32_16x16x32_bf16 v[24:27], v[148:151], v[164:167], v[24:27]
	v_mfma_f32_16x16x32_bf16 v[20:23], v[148:151], v[168:171], v[20:23]
	s_add_u32 m0, s4, 0x5000
	s_nop 0
	global_load_lds_dwordx4 v57, s[2:3]
	v_mfma_f32_16x16x32_bf16 v[16:19], v[152:155], v[156:159], v[16:19]
	v_mfma_f32_16x16x32_bf16 v[12:15], v[152:155], v[160:163], v[12:15]
	s_add_u32 m0, s4, 0x6000
	s_nop 0
	global_load_lds_dwordx4 v58, s[2:3]
	v_mfma_f32_16x16x32_bf16 v[8:11], v[152:155], v[164:167], v[8:11]
	v_mfma_f32_16x16x32_bf16 v[4:7], v[152:155], v[168:171], v[4:7]
	s_add_u32 m0, s4, 0x7000
	s_nop 0
	global_load_lds_dwordx4 v59, s[2:3]
	s_add_u32 s0, s0, 0x80
	s_addc_u32 s1, s1, 0
	s_add_u32 s2, s2, 0x80
	s_addc_u32 s3, s3, 0
	s_waitcnt vmcnt(0) lgkmcnt(0)
	s_barrier
	ds_read_b128 v[140:143], v66 offset:0
	ds_read_b128 v[144:147], v66 offset:2048
	ds_read_b128 v[148:151], v66 offset:4096
	ds_read_b128 v[152:155], v66 offset:6144
	ds_read_b128 v[156:159], v64 offset:0
	ds_read_b128 v[160:163], v64 offset:2048
	ds_read_b128 v[164:167], v64 offset:4096
	ds_read_b128 v[168:171], v64 offset:6144
	v_mfma_f32_16x16x32_bf16 v[60:63], v[172:175], v[188:191], v[60:63]
	v_mfma_f32_16x16x32_bf16 v[68:71], v[172:175], v[192:195], v[68:71]
	v_mfma_f32_16x16x32_bf16 v[52:55], v[172:175], v[196:199], v[52:55]
	v_mfma_f32_16x16x32_bf16 v[40:43], v[172:175], v[200:203], v[40:43]
	v_mfma_f32_16x16x32_bf16 v[72:75], v[176:179], v[188:191], v[72:75]
	v_mfma_f32_16x16x32_bf16 v[48:51], v[176:179], v[192:195], v[48:51]
	v_mfma_f32_16x16x32_bf16 v[44:47], v[176:179], v[196:199], v[44:47]
	v_mfma_f32_16x16x32_bf16 v[36:39], v[176:179], v[200:203], v[36:39]
	v_mfma_f32_16x16x32_bf16 v[32:35], v[180:183], v[188:191], v[32:35]
	v_mfma_f32_16x16x32_bf16 v[28:31], v[180:183], v[192:195], v[28:31]
	v_mfma_f32_16x16x32_bf16 v[24:27], v[180:183], v[196:199], v[24:27]
	v_mfma_f32_16x16x32_bf16 v[20:23], v[180:183], v[200:203], v[20:23]
	v_mfma_f32_16x16x32_bf16 v[16:19], v[184:187], v[188:191], v[16:19]
	v_mfma_f32_16x16x32_bf16 v[12:15], v[184:187], v[192:195], v[12:15]
	v_mfma_f32_16x16x32_bf16 v[8:11], v[184:187], v[196:199], v[8:11]
	v_mfma_f32_16x16x32_bf16 v[4:7], v[184:187], v[200:203], v[4:7]
	s_waitcnt lgkmcnt(0)
	ds_read_b128 v[172:175], v67 offset:0
	ds_read_b128 v[176:179], v67 offset:2048
	ds_read_b128 v[180:183], v67 offset:4096
	ds_read_b128 v[184:187], v67 offset:6144
	ds_read_b128 v[188:191], v65 offset:0
	ds_read_b128 v[192:195], v65 offset:2048
	ds_read_b128 v[196:199], v65 offset:4096
	ds_read_b128 v[200:203], v65 offset:6144
	v_mfma_f32_16x16x32_bf16 v[60:63], v[140:143], v[156:159], v[60:63]
	v_mfma_f32_16x16x32_bf16 v[68:71], v[140:143], v[160:163], v[68:71]
	s_add_u32 m0, s4, 0x8000
	s_nop 0
	global_load_lds_dwordx4 v56, s[0:1]
	v_mfma_f32_16x16x32_bf16 v[52:55], v[140:143], v[164:167], v[52:55]
	v_mfma_f32_16x16x32_bf16 v[40:43], v[140:143], v[168:171], v[40:43]
	s_add_u32 m0, s4, 0x9000
	s_nop 0
	global_load_lds_dwordx4 v57, s[0:1]
	v_mfma_f32_16x16x32_bf16 v[72:75], v[144:147], v[156:159], v[72:75]
	v_mfma_f32_16x16x32_bf16 v[48:51], v[144:147], v[160:163], v[48:51]
	s_add_u32 m0, s4, 0xa000
	s_nop 0
	global_load_lds_dwordx4 v58, s[0:1]
	v_mfma_f32_16x16x32_bf16 v[44:47], v[144:147], v[164:167], v[44:47]
	v_mfma_f32_16x16x32_bf16 v[36:39], v[144:147], v[168:171], v[36:39]
	s_add_u32 m0, s4, 0xb000
	s_nop 0
	global_load_lds_dwordx4 v59, s[0:1]
	v_mfma_f32_16x16x32_bf16 v[32:35], v[148:151], v[156:159], v[32:35]
	v_mfma_f32_16x16x32_bf16 v[28:31], v[148:151], v[160:163], v[28:31]
	s_add_u32 m0, s4, 0xc000
	s_nop 0
	global_load_lds_dwordx4 v56, s[2:3]
	v_mfma_f32_16x16x32_bf16 v[24:27], v[148:151], v[164:167], v[24:27]
	v_mfma_f32_16x16x32_bf16 v[20:23], v[148:151], v[168:171], v[20:23]
	s_add_u32 m0, s4, 0xd000
	s_nop 0
	global_load_lds_dwordx4 v57, s[2:3]
	v_mfma_f32_16x16x32_bf16 v[16:19], v[152:155], v[156:159], v[16:19]
	v_mfma_f32_16x16x32_bf16 v[12:15], v[152:155], v[160:163], v[12:15]
	s_add_u32 m0, s4, 0xe000
	s_nop 0
	global_load_lds_dwordx4 v58, s[2:3]
	v_mfma_f32_16x16x32_bf16 v[8:11], v[152:155], v[164:167], v[8:11]
	v_mfma_f32_16x16x32_bf16 v[4:7], v[152:155], v[168:171], v[4:7]
	s_add_u32 m0, s4, 0xf000
	s_nop 0
	global_load_lds_dwordx4 v59, s[2:3]
	s_add_u32 s0, s0, 0x80
	s_addc_u32 s1, s1, 0
	s_add_u32 s2, s2, 0x80
	s_addc_u32 s3, s3, 0
	s_waitcnt vmcnt(0) lgkmcnt(0)
	s_barrier
	ds_read_b128 v[140:143], v66 offset:32768
	ds_read_b128 v[144:147], v66 offset:34816
	ds_read_b128 v[148:151], v66 offset:36864
	ds_read_b128 v[152:155], v66 offset:38912
	ds_read_b128 v[156:159], v64 offset:32768
	ds_read_b128 v[160:163], v64 offset:34816
	ds_read_b128 v[164:167], v64 offset:36864
	ds_read_b128 v[168:171], v64 offset:38912
	v_mfma_f32_16x16x32_bf16 v[60:63], v[172:175], v[188:191], v[60:63]
	v_mfma_f32_16x16x32_bf16 v[68:71], v[172:175], v[192:195], v[68:71]
	v_mfma_f32_16x16x32_bf16 v[52:55], v[172:175], v[196:199], v[52:55]
	v_mfma_f32_16x16x32_bf16 v[40:43], v[172:175], v[200:203], v[40:43]
	v_mfma_f32_16x16x32_bf16 v[72:75], v[176:179], v[188:191], v[72:75]
	v_mfma_f32_16x16x32_bf16 v[48:51], v[176:179], v[192:195], v[48:51]
	v_mfma_f32_16x16x32_bf16 v[44:47], v[176:179], v[196:199], v[44:47]
	v_mfma_f32_16x16x32_bf16 v[36:39], v[176:179], v[200:203], v[36:39]
	v_mfma_f32_16x16x32_bf16 v[32:35], v[180:183], v[188:191], v[32:35]
	v_mfma_f32_16x16x32_bf16 v[28:31], v[180:183], v[192:195], v[28:31]
	v_mfma_f32_16x16x32_bf16 v[24:27], v[180:183], v[196:199], v[24:27]
	v_mfma_f32_16x16x32_bf16 v[20:23], v[180:183], v[200:203], v[20:23]
	v_mfma_f32_16x16x32_bf16 v[16:19], v[184:187], v[188:191], v[16:19]
	v_mfma_f32_16x16x32_bf16 v[12:15], v[184:187], v[192:195], v[12:15]
	v_mfma_f32_16x16x32_bf16 v[8:11], v[184:187], v[196:199], v[8:11]
	v_mfma_f32_16x16x32_bf16 v[4:7], v[184:187], v[200:203], v[4:7]
	s_waitcnt lgkmcnt(0)
	ds_read_b128 v[172:175], v67 offset:32768
	ds_read_b128 v[176:179], v67 offset:34816
	ds_read_b128 v[180:183], v67 offset:36864
	ds_read_b128 v[184:187], v67 offset:38912
	ds_read_b128 v[188:191], v65 offset:32768
	ds_read_b128 v[192:195], v65 offset:34816
	ds_read_b128 v[196:199], v65 offset:36864
	ds_read_b128 v[200:203], v65 offset:38912
	v_mfma_f32_16x16x32_bf16 v[60:63], v[140:143], v[156:159], v[60:63]
	v_mfma_f32_16x16x32_bf16 v[68:71], v[140:143], v[160:163], v[68:71]
	s_add_u32 m0, s4, 0x0
	s_nop 0
	global_load_lds_dwordx4 v56, s[0:1]
	v_mfma_f32_16x16x32_bf16 v[52:55], v[140:143], v[164:167], v[52:55]
	v_mfma_f32_16x16x32_bf16 v[40:43], v[140:143], v[168:171], v[40:43]
	s_add_u32 m0, s4, 0x1000
	s_nop 0
	global_load_lds_dwordx4 v57, s[0:1]
	v_mfma_f32_16x16x32_bf16 v[72:75], v[144:147], v[156:159], v[72:75]
	v_mfma_f32_16x16x32_bf16 v[48:51], v[144:147], v[160:163], v[48:51]
	s_add_u32 m0, s4, 0x2000
	s_nop 0
	global_load_lds_dwordx4 v58, s[0:1]
	v_mfma_f32_16x16x32_bf16 v[44:47], v[144:147], v[164:167], v[44:47]
	v_mfma_f32_16x16x32_bf16 v[36:39], v[144:147], v[168:171], v[36:39]
	s_add_u32 m0, s4, 0x3000
	s_nop 0
	global_load_lds_dwordx4 v59, s[0:1]
	v_mfma_f32_16x16x32_bf16 v[32:35], v[148:151], v[156:159], v[32:35]
	v_mfma_f32_16x16x32_bf16 v[28:31], v[148:151], v[160:163], v[28:31]
	s_add_u32 m0, s4, 0x4000
	s_nop 0
	global_load_lds_dwordx4 v56, s[2:3]
	v_mfma_f32_16x16x32_bf16 v[24:27], v[148:151], v[164:167], v[24:27]
	v_mfma_f32_16x16x32_bf16 v[20:23], v[148:151], v[168:171], v[20:23]
	s_add_u32 m0, s4, 0x5000
	s_nop 0
	global_load_lds_dwordx4 v57, s[2:3]
	v_mfma_f32_16x16x32_bf16 v[16:19], v[152:155], v[156:159], v[16:19]
	v_mfma_f32_16x16x32_bf16 v[12:15], v[152:155], v[160:163], v[12:15]
	s_add_u32 m0, s4, 0x6000
	s_nop 0
	global_load_lds_dwordx4 v58, s[2:3]
	v_mfma_f32_16x16x32_bf16 v[8:11], v[152:155], v[164:167], v[8:11]
	v_mfma_f32_16x16x32_bf16 v[4:7], v[152:155], v[168:171], v[4:7]
	s_add_u32 m0, s4, 0x7000
	s_nop 0
	global_load_lds_dwordx4 v59, s[2:3]
	s_add_u32 s0, s0, 0x80
	s_addc_u32 s1, s1, 0
	s_add_u32 s2, s2, 0x80
	s_addc_u32 s3, s3, 0
	s_waitcnt vmcnt(0) lgkmcnt(0)
	s_barrier
	ds_read_b128 v[140:143], v66 offset:0
	ds_read_b128 v[144:147], v66 offset:2048
	ds_read_b128 v[148:151], v66 offset:4096
	ds_read_b128 v[152:155], v66 offset:6144
	ds_read_b128 v[156:159], v64 offset:0
	ds_read_b128 v[160:163], v64 offset:2048
	ds_read_b128 v[164:167], v64 offset:4096
	ds_read_b128 v[168:171], v64 offset:6144
	v_mfma_f32_16x16x32_bf16 v[60:63], v[172:175], v[188:191], v[60:63]
	v_mfma_f32_16x16x32_bf16 v[68:71], v[172:175], v[192:195], v[68:71]
	v_mfma_f32_16x16x32_bf16 v[52:55], v[172:175], v[196:199], v[52:55]
	v_mfma_f32_16x16x32_bf16 v[40:43], v[172:175], v[200:203], v[40:43]
	v_mfma_f32_16x16x32_bf16 v[72:75], v[176:179], v[188:191], v[72:75]
	v_mfma_f32_16x16x32_bf16 v[48:51], v[176:179], v[192:195], v[48:51]
	v_mfma_f32_16x16x32_bf16 v[44:47], v[176:179], v[196:199], v[44:47]
	v_mfma_f32_16x16x32_bf16 v[36:39], v[176:179], v[200:203], v[36:39]
	v_mfma_f32_16x16x32_bf16 v[32:35], v[180:183], v[188:191], v[32:35]
	v_mfma_f32_16x16x32_bf16 v[28:31], v[180:183], v[192:195], v[28:31]
	v_mfma_f32_16x16x32_bf16 v[24:27], v[180:183], v[196:199], v[24:27]
	v_mfma_f32_16x16x32_bf16 v[20:23], v[180:183], v[200:203], v[20:23]
	v_mfma_f32_16x16x32_bf16 v[16:19], v[184:187], v[188:191], v[16:19]
	v_mfma_f32_16x16x32_bf16 v[12:15], v[184:187], v[192:195], v[12:15]
	v_mfma_f32_16x16x32_bf16 v[8:11], v[184:187], v[196:199], v[8:11]
	v_mfma_f32_16x16x32_bf16 v[4:7], v[184:187], v[200:203], v[4:7]
	s_waitcnt lgkmcnt(0)
	ds_read_b128 v[172:175], v67 offset:0
	ds_read_b128 v[176:179], v67 offset:2048
	ds_read_b128 v[180:183], v67 offset:4096
	ds_read_b128 v[184:187], v67 offset:6144
	ds_read_b128 v[188:191], v65 offset:0
	ds_read_b128 v[192:195], v65 offset:2048
	ds_read_b128 v[196:199], v65 offset:4096
	ds_read_b128 v[200:203], v65 offset:6144
	v_mfma_f32_16x16x32_bf16 v[60:63], v[140:143], v[156:159], v[60:63]
	v_mfma_f32_16x16x32_bf16 v[68:71], v[140:143], v[160:163], v[68:71]
	s_add_u32 m0, s4, 0x8000
	s_nop 0
	global_load_lds_dwordx4 v56, s[0:1]
	v_mfma_f32_16x16x32_bf16 v[52:55], v[140:143], v[164:167], v[52:55]
	v_mfma_f32_16x16x32_bf16 v[40:43], v[140:143], v[168:171], v[40:43]
	s_add_u32 m0, s4, 0x9000
	s_nop 0
	global_load_lds_dwordx4 v57, s[0:1]
	v_mfma_f32_16x16x32_bf16 v[72:75], v[144:147], v[156:159], v[72:75]
	v_mfma_f32_16x16x32_bf16 v[48:51], v[144:147], v[160:163], v[48:51]
	s_add_u32 m0, s4, 0xa000
	s_nop 0
	global_load_lds_dwordx4 v58, s[0:1]
	v_mfma_f32_16x16x32_bf16 v[44:47], v[144:147], v[164:167], v[44:47]
	v_mfma_f32_16x16x32_bf16 v[36:39], v[144:147], v[168:171], v[36:39]
	s_add_u32 m0, s4, 0xb000
	s_nop 0
	global_load_lds_dwordx4 v59, s[0:1]
	v_mfma_f32_16x16x32_bf16 v[32:35], v[148:151], v[156:159], v[32:35]
	v_mfma_f32_16x16x32_bf16 v[28:31], v[148:151], v[160:163], v[28:31]
	s_add_u32 m0, s4, 0xc000
	s_nop 0
	global_load_lds_dwordx4 v56, s[2:3]
	v_mfma_f32_16x16x32_bf16 v[24:27], v[148:151], v[164:167], v[24:27]
	v_mfma_f32_16x16x32_bf16 v[20:23], v[148:151], v[168:171], v[20:23]
	s_add_u32 m0, s4, 0xd000
	s_nop 0
	global_load_lds_dwordx4 v57, s[2:3]
	v_mfma_f32_16x16x32_bf16 v[16:19], v[152:155], v[156:159], v[16:19]
	v_mfma_f32_16x16x32_bf16 v[12:15], v[152:155], v[160:163], v[12:15]
	s_add_u32 m0, s4, 0xe000
	s_nop 0
	global_load_lds_dwordx4 v58, s[2:3]
	v_mfma_f32_16x16x32_bf16 v[8:11], v[152:155], v[164:167], v[8:11]
	v_mfma_f32_16x16x32_bf16 v[4:7], v[152:155], v[168:171], v[4:7]
	s_add_u32 m0, s4, 0xf000
	s_nop 0
	global_load_lds_dwordx4 v59, s[2:3]
	s_add_u32 s0, s0, 0x80
	s_addc_u32 s1, s1, 0
	s_add_u32 s2, s2, 0x80
	s_addc_u32 s3, s3, 0
	s_waitcnt vmcnt(0) lgkmcnt(0)
	s_barrier
	ds_read_b128 v[140:143], v66 offset:32768
	ds_read_b128 v[144:147], v66 offset:34816
	ds_read_b128 v[148:151], v66 offset:36864
	ds_read_b128 v[152:155], v66 offset:38912
	ds_read_b128 v[156:159], v64 offset:32768
	ds_read_b128 v[160:163], v64 offset:34816
	ds_read_b128 v[164:167], v64 offset:36864
	ds_read_b128 v[168:171], v64 offset:38912
	v_mfma_f32_16x16x32_bf16 v[60:63], v[172:175], v[188:191], v[60:63]
	v_mfma_f32_16x16x32_bf16 v[68:71], v[172:175], v[192:195], v[68:71]
	v_mfma_f32_16x16x32_bf16 v[52:55], v[172:175], v[196:199], v[52:55]
	v_mfma_f32_16x16x32_bf16 v[40:43], v[172:175], v[200:203], v[40:43]
	v_mfma_f32_16x16x32_bf16 v[72:75], v[176:179], v[188:191], v[72:75]
	v_mfma_f32_16x16x32_bf16 v[48:51], v[176:179], v[192:195], v[48:51]
	v_mfma_f32_16x16x32_bf16 v[44:47], v[176:179], v[196:199], v[44:47]
	v_mfma_f32_16x16x32_bf16 v[36:39], v[176:179], v[200:203], v[36:39]
	v_mfma_f32_16x16x32_bf16 v[32:35], v[180:183], v[188:191], v[32:35]
	v_mfma_f32_16x16x32_bf16 v[28:31], v[180:183], v[192:195], v[28:31]
	v_mfma_f32_16x16x32_bf16 v[24:27], v[180:183], v[196:199], v[24:27]
	v_mfma_f32_16x16x32_bf16 v[20:23], v[180:183], v[200:203], v[20:23]
	v_mfma_f32_16x16x32_bf16 v[16:19], v[184:187], v[188:191], v[16:19]
	v_mfma_f32_16x16x32_bf16 v[12:15], v[184:187], v[192:195], v[12:15]
	v_mfma_f32_16x16x32_bf16 v[8:11], v[184:187], v[196:199], v[8:11]
	v_mfma_f32_16x16x32_bf16 v[4:7], v[184:187], v[200:203], v[4:7]
	s_waitcnt lgkmcnt(0)
	ds_read_b128 v[172:175], v67 offset:32768
	ds_read_b128 v[176:179], v67 offset:34816
	ds_read_b128 v[180:183], v67 offset:36864
	ds_read_b128 v[184:187], v67 offset:38912
	ds_read_b128 v[188:191], v65 offset:32768
	ds_read_b128 v[192:195], v65 offset:34816
	ds_read_b128 v[196:199], v65 offset:36864
	ds_read_b128 v[200:203], v65 offset:38912
	v_mfma_f32_16x16x32_bf16 v[60:63], v[140:143], v[156:159], v[60:63]
	v_mfma_f32_16x16x32_bf16 v[68:71], v[140:143], v[160:163], v[68:71]
	s_add_u32 m0, s4, 0x0
	s_nop 0
	global_load_lds_dwordx4 v56, s[0:1]
	v_mfma_f32_16x16x32_bf16 v[52:55], v[140:143], v[164:167], v[52:55]
	v_mfma_f32_16x16x32_bf16 v[40:43], v[140:143], v[168:171], v[40:43]
	s_add_u32 m0, s4, 0x1000
	s_nop 0
	global_load_lds_dwordx4 v57, s[0:1]
	v_mfma_f32_16x16x32_bf16 v[72:75], v[144:147], v[156:159], v[72:75]
	v_mfma_f32_16x16x32_bf16 v[48:51], v[144:147], v[160:163], v[48:51]
	s_add_u32 m0, s4, 0x2000
	s_nop 0
	global_load_lds_dwordx4 v58, s[0:1]
	v_mfma_f32_16x16x32_bf16 v[44:47], v[144:147], v[164:167], v[44:47]
	v_mfma_f32_16x16x32_bf16 v[36:39], v[144:147], v[168:171], v[36:39]
	s_add_u32 m0, s4, 0x3000
	s_nop 0
	global_load_lds_dwordx4 v59, s[0:1]
	v_mfma_f32_16x16x32_bf16 v[32:35], v[148:151], v[156:159], v[32:35]
	v_mfma_f32_16x16x32_bf16 v[28:31], v[148:151], v[160:163], v[28:31]
	s_add_u32 m0, s4, 0x4000
	s_nop 0
	global_load_lds_dwordx4 v56, s[2:3]
	v_mfma_f32_16x16x32_bf16 v[24:27], v[148:151], v[164:167], v[24:27]
	v_mfma_f32_16x16x32_bf16 v[20:23], v[148:151], v[168:171], v[20:23]
	s_add_u32 m0, s4, 0x5000
	s_nop 0
	global_load_lds_dwordx4 v57, s[2:3]
	v_mfma_f32_16x16x32_bf16 v[16:19], v[152:155], v[156:159], v[16:19]
	v_mfma_f32_16x16x32_bf16 v[12:15], v[152:155], v[160:163], v[12:15]
	s_add_u32 m0, s4, 0x6000
	s_nop 0
	global_load_lds_dwordx4 v58, s[2:3]
	v_mfma_f32_16x16x32_bf16 v[8:11], v[152:155], v[164:167], v[8:11]
	v_mfma_f32_16x16x32_bf16 v[4:7], v[152:155], v[168:171], v[4:7]
	s_add_u32 m0, s4, 0x7000
	s_nop 0
	global_load_lds_dwordx4 v59, s[2:3]
	s_add_u32 s0, s0, 0x80
	s_addc_u32 s1, s1, 0
	s_add_u32 s2, s2, 0x80
	s_addc_u32 s3, s3, 0
	s_waitcnt vmcnt(0) lgkmcnt(0)
	s_barrier
	ds_read_b128 v[140:143], v66 offset:0
	ds_read_b128 v[144:147], v66 offset:2048
	ds_read_b128 v[148:151], v66 offset:4096
	ds_read_b128 v[152:155], v66 offset:6144
	ds_read_b128 v[156:159], v64 offset:0
	ds_read_b128 v[160:163], v64 offset:2048
	ds_read_b128 v[164:167], v64 offset:4096
	ds_read_b128 v[168:171], v64 offset:6144
	v_mfma_f32_16x16x32_bf16 v[60:63], v[172:175], v[188:191], v[60:63]
	v_mfma_f32_16x16x32_bf16 v[68:71], v[172:175], v[192:195], v[68:71]
	v_mfma_f32_16x16x32_bf16 v[52:55], v[172:175], v[196:199], v[52:55]
	v_mfma_f32_16x16x32_bf16 v[40:43], v[172:175], v[200:203], v[40:43]
	v_mfma_f32_16x16x32_bf16 v[72:75], v[176:179], v[188:191], v[72:75]
	v_mfma_f32_16x16x32_bf16 v[48:51], v[176:179], v[192:195], v[48:51]
	v_mfma_f32_16x16x32_bf16 v[44:47], v[176:179], v[196:199], v[44:47]
	v_mfma_f32_16x16x32_bf16 v[36:39], v[176:179], v[200:203], v[36:39]
	v_mfma_f32_16x16x32_bf16 v[32:35], v[180:183], v[188:191], v[32:35]
	v_mfma_f32_16x16x32_bf16 v[28:31], v[180:183], v[192:195], v[28:31]
	v_mfma_f32_16x16x32_bf16 v[24:27], v[180:183], v[196:199], v[24:27]
	v_mfma_f32_16x16x32_bf16 v[20:23], v[180:183], v[200:203], v[20:23]
	v_mfma_f32_16x16x32_bf16 v[16:19], v[184:187], v[188:191], v[16:19]
	v_mfma_f32_16x16x32_bf16 v[12:15], v[184:187], v[192:195], v[12:15]
	v_mfma_f32_16x16x32_bf16 v[8:11], v[184:187], v[196:199], v[8:11]
	v_mfma_f32_16x16x32_bf16 v[4:7], v[184:187], v[200:203], v[4:7]
	s_waitcnt lgkmcnt(0)
	ds_read_b128 v[172:175], v67 offset:0
	ds_read_b128 v[176:179], v67 offset:2048
	ds_read_b128 v[180:183], v67 offset:4096
	ds_read_b128 v[184:187], v67 offset:6144
	ds_read_b128 v[188:191], v65 offset:0
	ds_read_b128 v[192:195], v65 offset:2048
	ds_read_b128 v[196:199], v65 offset:4096
	ds_read_b128 v[200:203], v65 offset:6144
	v_mfma_f32_16x16x32_bf16 v[60:63], v[140:143], v[156:159], v[60:63]
	v_mfma_f32_16x16x32_bf16 v[68:71], v[140:143], v[160:163], v[68:71]
	s_add_u32 m0, s4, 0x8000
	s_nop 0
	global_load_lds_dwordx4 v56, s[0:1]
	v_mfma_f32_16x16x32_bf16 v[52:55], v[140:143], v[164:167], v[52:55]
	v_mfma_f32_16x16x32_bf16 v[40:43], v[140:143], v[168:171], v[40:43]
	s_add_u32 m0, s4, 0x9000
	s_nop 0
	global_load_lds_dwordx4 v57, s[0:1]
	v_mfma_f32_16x16x32_bf16 v[72:75], v[144:147], v[156:159], v[72:75]
	v_mfma_f32_16x16x32_bf16 v[48:51], v[144:147], v[160:163], v[48:51]
	s_add_u32 m0, s4, 0xa000
	s_nop 0
	global_load_lds_dwordx4 v58, s[0:1]
	v_mfma_f32_16x16x32_bf16 v[44:47], v[144:147], v[164:167], v[44:47]
	v_mfma_f32_16x16x32_bf16 v[36:39], v[144:147], v[168:171], v[36:39]
	s_add_u32 m0, s4, 0xb000
	s_nop 0
	global_load_lds_dwordx4 v59, s[0:1]
	v_mfma_f32_16x16x32_bf16 v[32:35], v[148:151], v[156:159], v[32:35]
	v_mfma_f32_16x16x32_bf16 v[28:31], v[148:151], v[160:163], v[28:31]
	s_add_u32 m0, s4, 0xc000
	s_nop 0
	global_load_lds_dwordx4 v56, s[2:3]
	v_mfma_f32_16x16x32_bf16 v[24:27], v[148:151], v[164:167], v[24:27]
	v_mfma_f32_16x16x32_bf16 v[20:23], v[148:151], v[168:171], v[20:23]
	s_add_u32 m0, s4, 0xd000
	s_nop 0
	global_load_lds_dwordx4 v57, s[2:3]
	v_mfma_f32_16x16x32_bf16 v[16:19], v[152:155], v[156:159], v[16:19]
	v_mfma_f32_16x16x32_bf16 v[12:15], v[152:155], v[160:163], v[12:15]
	s_add_u32 m0, s4, 0xe000
	s_nop 0
	global_load_lds_dwordx4 v58, s[2:3]
	v_mfma_f32_16x16x32_bf16 v[8:11], v[152:155], v[164:167], v[8:11]
	v_mfma_f32_16x16x32_bf16 v[4:7], v[152:155], v[168:171], v[4:7]
	s_add_u32 m0, s4, 0xf000
	s_nop 0
	global_load_lds_dwordx4 v59, s[2:3]
	s_add_u32 s0, s0, 0x80
	s_addc_u32 s1, s1, 0
	s_add_u32 s2, s2, 0x80
	s_addc_u32 s3, s3, 0
	s_waitcnt vmcnt(0) lgkmcnt(0)
	s_barrier
	ds_read_b128 v[140:143], v66 offset:32768
	ds_read_b128 v[144:147], v66 offset:34816
	ds_read_b128 v[148:151], v66 offset:36864
	ds_read_b128 v[152:155], v66 offset:38912
	ds_read_b128 v[156:159], v64 offset:32768
	ds_read_b128 v[160:163], v64 offset:34816
	ds_read_b128 v[164:167], v64 offset:36864
	ds_read_b128 v[168:171], v64 offset:38912
	v_mfma_f32_16x16x32_bf16 v[60:63], v[172:175], v[188:191], v[60:63]
	v_mfma_f32_16x16x32_bf16 v[68:71], v[172:175], v[192:195], v[68:71]
	v_mfma_f32_16x16x32_bf16 v[52:55], v[172:175], v[196:199], v[52:55]
	v_mfma_f32_16x16x32_bf16 v[40:43], v[172:175], v[200:203], v[40:43]
	v_mfma_f32_16x16x32_bf16 v[72:75], v[176:179], v[188:191], v[72:75]
	v_mfma_f32_16x16x32_bf16 v[48:51], v[176:179], v[192:195], v[48:51]
	v_mfma_f32_16x16x32_bf16 v[44:47], v[176:179], v[196:199], v[44:47]
	v_mfma_f32_16x16x32_bf16 v[36:39], v[176:179], v[200:203], v[36:39]
	v_mfma_f32_16x16x32_bf16 v[32:35], v[180:183], v[188:191], v[32:35]
	v_mfma_f32_16x16x32_bf16 v[28:31], v[180:183], v[192:195], v[28:31]
	v_mfma_f32_16x16x32_bf16 v[24:27], v[180:183], v[196:199], v[24:27]
	v_mfma_f32_16x16x32_bf16 v[20:23], v[180:183], v[200:203], v[20:23]
	v_mfma_f32_16x16x32_bf16 v[16:19], v[184:187], v[188:191], v[16:19]
	v_mfma_f32_16x16x32_bf16 v[12:15], v[184:187], v[192:195], v[12:15]
	v_mfma_f32_16x16x32_bf16 v[8:11], v[184:187], v[196:199], v[8:11]
	v_mfma_f32_16x16x32_bf16 v[4:7], v[184:187], v[200:203], v[4:7]
	s_waitcnt lgkmcnt(0)
	ds_read_b128 v[172:175], v67 offset:32768
	ds_read_b128 v[176:179], v67 offset:34816
	ds_read_b128 v[180:183], v67 offset:36864
	ds_read_b128 v[184:187], v67 offset:38912
	ds_read_b128 v[188:191], v65 offset:32768
	ds_read_b128 v[192:195], v65 offset:34816
	ds_read_b128 v[196:199], v65 offset:36864
	ds_read_b128 v[200:203], v65 offset:38912
	v_mfma_f32_16x16x32_bf16 v[60:63], v[140:143], v[156:159], v[60:63]
	v_mfma_f32_16x16x32_bf16 v[68:71], v[140:143], v[160:163], v[68:71]
	s_add_u32 m0, s4, 0x0
	s_nop 0
	global_load_lds_dwordx4 v56, s[0:1]
	v_mfma_f32_16x16x32_bf16 v[52:55], v[140:143], v[164:167], v[52:55]
	v_mfma_f32_16x16x32_bf16 v[40:43], v[140:143], v[168:171], v[40:43]
	s_add_u32 m0, s4, 0x1000
	s_nop 0
	global_load_lds_dwordx4 v57, s[0:1]
	v_mfma_f32_16x16x32_bf16 v[72:75], v[144:147], v[156:159], v[72:75]
	v_mfma_f32_16x16x32_bf16 v[48:51], v[144:147], v[160:163], v[48:51]
	s_add_u32 m0, s4, 0x2000
	s_nop 0
	global_load_lds_dwordx4 v58, s[0:1]
	v_mfma_f32_16x16x32_bf16 v[44:47], v[144:147], v[164:167], v[44:47]
	v_mfma_f32_16x16x32_bf16 v[36:39], v[144:147], v[168:171], v[36:39]
	s_add_u32 m0, s4, 0x3000
	s_nop 0
	global_load_lds_dwordx4 v59, s[0:1]
	v_mfma_f32_16x16x32_bf16 v[32:35], v[148:151], v[156:159], v[32:35]
	v_mfma_f32_16x16x32_bf16 v[28:31], v[148:151], v[160:163], v[28:31]
	s_add_u32 m0, s4, 0x4000
	s_nop 0
	global_load_lds_dwordx4 v56, s[2:3]
	v_mfma_f32_16x16x32_bf16 v[24:27], v[148:151], v[164:167], v[24:27]
	v_mfma_f32_16x16x32_bf16 v[20:23], v[148:151], v[168:171], v[20:23]
	s_add_u32 m0, s4, 0x5000
	s_nop 0
	global_load_lds_dwordx4 v57, s[2:3]
	v_mfma_f32_16x16x32_bf16 v[16:19], v[152:155], v[156:159], v[16:19]
	v_mfma_f32_16x16x32_bf16 v[12:15], v[152:155], v[160:163], v[12:15]
	s_add_u32 m0, s4, 0x6000
	s_nop 0
	global_load_lds_dwordx4 v58, s[2:3]
	v_mfma_f32_16x16x32_bf16 v[8:11], v[152:155], v[164:167], v[8:11]
	v_mfma_f32_16x16x32_bf16 v[4:7], v[152:155], v[168:171], v[4:7]
	s_add_u32 m0, s4, 0x7000
	s_nop 0
	global_load_lds_dwordx4 v59, s[2:3]
	s_add_u32 s0, s0, 0x80
	s_addc_u32 s1, s1, 0
	s_add_u32 s2, s2, 0x80
	s_addc_u32 s3, s3, 0
	s_waitcnt vmcnt(0) lgkmcnt(0)
	s_barrier
	ds_read_b128 v[140:143], v66 offset:0
	ds_read_b128 v[144:147], v66 offset:2048
	ds_read_b128 v[148:151], v66 offset:4096
	ds_read_b128 v[152:155], v66 offset:6144
	ds_read_b128 v[156:159], v64 offset:0
	ds_read_b128 v[160:163], v64 offset:2048
	ds_read_b128 v[164:167], v64 offset:4096
	ds_read_b128 v[168:171], v64 offset:6144
	v_mfma_f32_16x16x32_bf16 v[60:63], v[172:175], v[188:191], v[60:63]
	v_mfma_f32_16x16x32_bf16 v[68:71], v[172:175], v[192:195], v[68:71]
	v_mfma_f32_16x16x32_bf16 v[52:55], v[172:175], v[196:199], v[52:55]
	v_mfma_f32_16x16x32_bf16 v[40:43], v[172:175], v[200:203], v[40:43]
	v_mfma_f32_16x16x32_bf16 v[72:75], v[176:179], v[188:191], v[72:75]
	v_mfma_f32_16x16x32_bf16 v[48:51], v[176:179], v[192:195], v[48:51]
	v_mfma_f32_16x16x32_bf16 v[44:47], v[176:179], v[196:199], v[44:47]
	v_mfma_f32_16x16x32_bf16 v[36:39], v[176:179], v[200:203], v[36:39]
	v_mfma_f32_16x16x32_bf16 v[32:35], v[180:183], v[188:191], v[32:35]
	v_mfma_f32_16x16x32_bf16 v[28:31], v[180:183], v[192:195], v[28:31]
	v_mfma_f32_16x16x32_bf16 v[24:27], v[180:183], v[196:199], v[24:27]
	v_mfma_f32_16x16x32_bf16 v[20:23], v[180:183], v[200:203], v[20:23]
	v_mfma_f32_16x16x32_bf16 v[16:19], v[184:187], v[188:191], v[16:19]
	v_mfma_f32_16x16x32_bf16 v[12:15], v[184:187], v[192:195], v[12:15]
	v_mfma_f32_16x16x32_bf16 v[8:11], v[184:187], v[196:199], v[8:11]
	v_mfma_f32_16x16x32_bf16 v[4:7], v[184:187], v[200:203], v[4:7]
	s_waitcnt lgkmcnt(0)
	ds_read_b128 v[172:175], v67 offset:0
	ds_read_b128 v[176:179], v67 offset:2048
	ds_read_b128 v[180:183], v67 offset:4096
	ds_read_b128 v[184:187], v67 offset:6144
	ds_read_b128 v[188:191], v65 offset:0
	ds_read_b128 v[192:195], v65 offset:2048
	ds_read_b128 v[196:199], v65 offset:4096
	ds_read_b128 v[200:203], v65 offset:6144
	v_mfma_f32_16x16x32_bf16 v[60:63], v[140:143], v[156:159], v[60:63]
	v_mfma_f32_16x16x32_bf16 v[68:71], v[140:143], v[160:163], v[68:71]
	s_add_u32 m0, s4, 0x8000
	s_nop 0
	global_load_lds_dwordx4 v56, s[0:1]
	v_mfma_f32_16x16x32_bf16 v[52:55], v[140:143], v[164:167], v[52:55]
	v_mfma_f32_16x16x32_bf16 v[40:43], v[140:143], v[168:171], v[40:43]
	s_add_u32 m0, s4, 0x9000
	s_nop 0
	global_load_lds_dwordx4 v57, s[0:1]
	v_mfma_f32_16x16x32_bf16 v[72:75], v[144:147], v[156:159], v[72:75]
	v_mfma_f32_16x16x32_bf16 v[48:51], v[144:147], v[160:163], v[48:51]
	s_add_u32 m0, s4, 0xa000
	s_nop 0
	global_load_lds_dwordx4 v58, s[0:1]
	v_mfma_f32_16x16x32_bf16 v[44:47], v[144:147], v[164:167], v[44:47]
	v_mfma_f32_16x16x32_bf16 v[36:39], v[144:147], v[168:171], v[36:39]
	s_add_u32 m0, s4, 0xb000
	s_nop 0
	global_load_lds_dwordx4 v59, s[0:1]
	v_mfma_f32_16x16x32_bf16 v[32:35], v[148:151], v[156:159], v[32:35]
	v_mfma_f32_16x16x32_bf16 v[28:31], v[148:151], v[160:163], v[28:31]
	s_add_u32 m0, s4, 0xc000
	s_nop 0
	global_load_lds_dwordx4 v56, s[2:3]
	v_mfma_f32_16x16x32_bf16 v[24:27], v[148:151], v[164:167], v[24:27]
	v_mfma_f32_16x16x32_bf16 v[20:23], v[148:151], v[168:171], v[20:23]
	s_add_u32 m0, s4, 0xd000
	s_nop 0
	global_load_lds_dwordx4 v57, s[2:3]
	v_mfma_f32_16x16x32_bf16 v[16:19], v[152:155], v[156:159], v[16:19]
	v_mfma_f32_16x16x32_bf16 v[12:15], v[152:155], v[160:163], v[12:15]
	s_add_u32 m0, s4, 0xe000
	s_nop 0
	global_load_lds_dwordx4 v58, s[2:3]
	v_mfma_f32_16x16x32_bf16 v[8:11], v[152:155], v[164:167], v[8:11]
	v_mfma_f32_16x16x32_bf16 v[4:7], v[152:155], v[168:171], v[4:7]
	s_add_u32 m0, s4, 0xf000
	s_nop 0
	global_load_lds_dwordx4 v59, s[2:3]
	s_add_u32 s0, s0, 0x80
	s_addc_u32 s1, s1, 0
	s_add_u32 s2, s2, 0x80
	s_addc_u32 s3, s3, 0
	s_waitcnt vmcnt(0) lgkmcnt(0)
	s_barrier
	ds_read_b128 v[140:143], v66 offset:32768
	ds_read_b128 v[144:147], v66 offset:34816
	ds_read_b128 v[148:151], v66 offset:36864
	ds_read_b128 v[152:155], v66 offset:38912
	ds_read_b128 v[156:159], v64 offset:32768
	ds_read_b128 v[160:163], v64 offset:34816
	ds_read_b128 v[164:167], v64 offset:36864
	ds_read_b128 v[168:171], v64 offset:38912
	v_mfma_f32_16x16x32_bf16 v[60:63], v[172:175], v[188:191], v[60:63]
	v_mfma_f32_16x16x32_bf16 v[68:71], v[172:175], v[192:195], v[68:71]
	v_mfma_f32_16x16x32_bf16 v[52:55], v[172:175], v[196:199], v[52:55]
	v_mfma_f32_16x16x32_bf16 v[40:43], v[172:175], v[200:203], v[40:43]
	v_mfma_f32_16x16x32_bf16 v[72:75], v[176:179], v[188:191], v[72:75]
	v_mfma_f32_16x16x32_bf16 v[48:51], v[176:179], v[192:195], v[48:51]
	v_mfma_f32_16x16x32_bf16 v[44:47], v[176:179], v[196:199], v[44:47]
	v_mfma_f32_16x16x32_bf16 v[36:39], v[176:179], v[200:203], v[36:39]
	v_mfma_f32_16x16x32_bf16 v[32:35], v[180:183], v[188:191], v[32:35]
	v_mfma_f32_16x16x32_bf16 v[28:31], v[180:183], v[192:195], v[28:31]
	v_mfma_f32_16x16x32_bf16 v[24:27], v[180:183], v[196:199], v[24:27]
	v_mfma_f32_16x16x32_bf16 v[20:23], v[180:183], v[200:203], v[20:23]
	v_mfma_f32_16x16x32_bf16 v[16:19], v[184:187], v[188:191], v[16:19]
	v_mfma_f32_16x16x32_bf16 v[12:15], v[184:187], v[192:195], v[12:15]
	v_mfma_f32_16x16x32_bf16 v[8:11], v[184:187], v[196:199], v[8:11]
	v_mfma_f32_16x16x32_bf16 v[4:7], v[184:187], v[200:203], v[4:7]
	s_waitcnt lgkmcnt(0)
	ds_read_b128 v[172:175], v67 offset:32768
	ds_read_b128 v[176:179], v67 offset:34816
	ds_read_b128 v[180:183], v67 offset:36864
	ds_read_b128 v[184:187], v67 offset:38912
	ds_read_b128 v[188:191], v65 offset:32768
	ds_read_b128 v[192:195], v65 offset:34816
	ds_read_b128 v[196:199], v65 offset:36864
	ds_read_b128 v[200:203], v65 offset:38912
	v_mfma_f32_16x16x32_bf16 v[60:63], v[140:143], v[156:159], v[60:63]
	v_mfma_f32_16x16x32_bf16 v[68:71], v[140:143], v[160:163], v[68:71]
	v_mfma_f32_16x16x32_bf16 v[52:55], v[140:143], v[164:167], v[52:55]
	v_mfma_f32_16x16x32_bf16 v[40:43], v[140:143], v[168:171], v[40:43]
	v_mfma_f32_16x16x32_bf16 v[72:75], v[144:147], v[156:159], v[72:75]
	v_mfma_f32_16x16x32_bf16 v[48:51], v[144:147], v[160:163], v[48:51]
	v_mfma_f32_16x16x32_bf16 v[44:47], v[144:147], v[164:167], v[44:47]
	v_mfma_f32_16x16x32_bf16 v[36:39], v[144:147], v[168:171], v[36:39]
	v_mfma_f32_16x16x32_bf16 v[32:35], v[148:151], v[156:159], v[32:35]
	v_mfma_f32_16x16x32_bf16 v[28:31], v[148:151], v[160:163], v[28:31]
	v_mfma_f32_16x16x32_bf16 v[24:27], v[148:151], v[164:167], v[24:27]
	v_mfma_f32_16x16x32_bf16 v[20:23], v[148:151], v[168:171], v[20:23]
	v_mfma_f32_16x16x32_bf16 v[16:19], v[152:155], v[156:159], v[16:19]
	v_mfma_f32_16x16x32_bf16 v[12:15], v[152:155], v[160:163], v[12:15]
	v_mfma_f32_16x16x32_bf16 v[8:11], v[152:155], v[164:167], v[8:11]
	v_mfma_f32_16x16x32_bf16 v[4:7], v[152:155], v[168:171], v[4:7]
	s_waitcnt vmcnt(0) lgkmcnt(0)
	s_barrier
	v_mfma_f32_16x16x32_bf16 v[60:63], v[172:175], v[188:191], v[60:63]
	v_mfma_f32_16x16x32_bf16 v[68:71], v[172:175], v[192:195], v[68:71]
	v_mfma_f32_16x16x32_bf16 v[52:55], v[172:175], v[196:199], v[52:55]
	v_mfma_f32_16x16x32_bf16 v[40:43], v[172:175], v[200:203], v[40:43]
	v_mfma_f32_16x16x32_bf16 v[72:75], v[176:179], v[188:191], v[72:75]
	v_mfma_f32_16x16x32_bf16 v[48:51], v[176:179], v[192:195], v[48:51]
	v_mfma_f32_16x16x32_bf16 v[44:47], v[176:179], v[196:199], v[44:47]
	v_mfma_f32_16x16x32_bf16 v[36:39], v[176:179], v[200:203], v[36:39]
	v_mfma_f32_16x16x32_bf16 v[32:35], v[180:183], v[188:191], v[32:35]
	v_mfma_f32_16x16x32_bf16 v[28:31], v[180:183], v[192:195], v[28:31]
	v_mfma_f32_16x16x32_bf16 v[24:27], v[180:183], v[196:199], v[24:27]
	v_mfma_f32_16x16x32_bf16 v[20:23], v[180:183], v[200:203], v[20:23]
	v_mfma_f32_16x16x32_bf16 v[16:19], v[184:187], v[188:191], v[16:19]
	v_mfma_f32_16x16x32_bf16 v[12:15], v[184:187], v[192:195], v[12:15]
	v_mfma_f32_16x16x32_bf16 v[8:11], v[184:187], v[196:199], v[8:11]
	v_mfma_f32_16x16x32_bf16 v[4:7], v[184:187], v[200:203], v[4:7]
	s_lshl_b32 s8, s22, 7
	v_cmp_gt_i32_e32 vcc, s19, v94
	s_nop 7
	s_nop 1
	s_and_saveexec_b64 s[0:1], vcc
	s_cbranch_execz .LBB0_423
	s_xor_b64 s[4:5], s[58:59], -1
	s_and_b32 s9, s64, 0x1fffffe
	s_cmp_lt_i32 s9, 12
	s_cbranch_scc1 .LBB0_349
	s_cmp_eq_u32 s9, 12
	s_cselect_b64 s[2:3], -1, 0
	s_cbranch_execz .LBB0_350
	s_branch .LBB0_351
